# v28
# speedup vs baseline: 1.0062x; 1.0020x over previous
.LBB0_499:
	s_andn2_saveexec_b64 s[12:13], s[28:29]
	s_cbranch_execz .LBB0_534
	s_cmp_eq_u32 s26, -16
	s_cbranch_scc1 .LBB0_534
	s_bitcmp1_b32 s34, 0
	s_cselect_b32 s28, 0x5180, 0
	v_add_u32_e32 v50, s28, v72
	v_lshl_add_u32 v59, v74, 2, v50
	s_waitcnt lgkmcnt(0)
	ds_read_b128 v[34:37], v59
	ds_read_b128 v[38:41], v59 offset:32
	ds_read_b128 v[42:45], v59 offset:768
	ds_read_b128 v[162:165], v59 offset:800
	ds_read_b128 v[166:169], v59 offset:64
	ds_read_b128 v[170:173], v59 offset:96
	ds_read_b128 v[174:177], v59 offset:832
	ds_read_b128 v[178:181], v59 offset:864
	ds_read_b128 v[182:185], v59 offset:128
	ds_read_b128 v[186:189], v59 offset:160
	ds_read_b128 v[190:193], v59 offset:192
	ds_read_b128 v[194:197], v59 offset:224
	s_waitcnt lgkmcnt(11)
	v_pk_fma_f32 v[36:37], v[2:3], v[36:37], 0 op_sel_hi:[1,1,0]
	v_pk_fma_f32 v[34:35], v[0:1], v[34:35], 0 op_sel_hi:[1,1,0]
	s_waitcnt lgkmcnt(3)
	v_pk_fma_f32 v[46:47], v[18:19], v[184:185], 0 op_sel_hi:[1,1,0]
	v_pk_fma_f32 v[182:183], v[16:17], v[182:183], 0 op_sel_hi:[1,1,0]
	v_pk_fma_f32 v[36:37], v[6:7], v[40:41], v[36:37]
	v_pk_fma_f32 v[34:35], v[4:5], v[38:39], v[34:35]
	s_waitcnt lgkmcnt(2)
	v_pk_fma_f32 v[38:39], v[22:23], v[188:189], v[46:47]
	v_lshl_add_u32 v61, v102, 2, v50
	v_pk_fma_f32 v[40:41], v[20:21], v[186:187], v[182:183]
	v_pk_fma_f32 v[36:37], v[10:11], v[168:169], v[36:37]
	v_pk_fma_f32 v[34:35], v[8:9], v[166:167], v[34:35]
	s_waitcnt lgkmcnt(1)
	v_pk_fma_f32 v[38:39], v[26:27], v[192:193], v[38:39]
	ds_read2_b32 v[198:199], v61 offset0:64 offset1:96
	v_pk_fma_f32 v[40:41], v[24:25], v[190:191], v[40:41]
	v_pk_fma_f32 v[36:37], v[14:15], v[172:173], v[36:37]
	v_pk_fma_f32 v[34:35], v[12:13], v[170:171], v[34:35]
	s_waitcnt lgkmcnt(1)
	v_pk_fma_f32 v[38:39], v[30:31], v[196:197], v[38:39]
	v_pk_fma_f32 v[40:41], v[28:29], v[194:195], v[40:41]
	v_add_f32_e32 v32, v34, v35
	v_add_f32_e32 v34, v36, v37
	v_add_f32_e32 v35, v38, v39
	v_pk_fma_f32 v[36:37], v[2:3], v[44:45], 0 op_sel_hi:[1,1,0]
	v_pk_fma_f32 v[38:39], v[0:1], v[42:43], 0 op_sel_hi:[1,1,0]
	v_lshl_add_u32 v158, v75, 2, v50
	v_add_f32_e32 v32, v32, v34
	v_add_f32_e32 v34, v40, v41
	v_pk_fma_f32 v[36:37], v[6:7], v[164:165], v[36:37]
	v_pk_fma_f32 v[38:39], v[4:5], v[162:163], v[38:39]
	ds_read_b32 v33, v158 offset:1024
	ds_read_b64 v[170:171], v50 offset:20736
	v_add_f32_e32 v34, v34, v35
	v_pk_fma_f32 v[36:37], v[10:11], v[176:177], v[36:37]
	v_pk_fma_f32 v[38:39], v[8:9], v[174:175], v[38:39]
	v_add_f32_e32 v32, v32, v34
	v_pk_fma_f32 v[166:167], v[14:15], v[180:181], v[36:37]
	v_pk_fma_f32 v[168:169], v[12:13], v[178:179], v[38:39]
	ds_read_b128 v[36:39], v59 offset:896
	ds_read_b128 v[40:43], v59 offset:928
	ds_read_b128 v[44:47], v59 offset:960
	ds_read_b128 v[162:165], v59 offset:992
	v_mov_b32_e32 v34, v32
	s_nop 1
	v_permlane32_swap_b32_e32 v32, v34
	s_waitcnt lgkmcnt(3)
	v_pk_fma_f32 v[38:39], v[18:19], v[38:39], 0 op_sel_hi:[1,1,0]
	v_pk_fma_f32 v[36:37], v[16:17], v[36:37], 0 op_sel_hi:[1,1,0]
	v_add_f32_e32 v35, v32, v34
	s_waitcnt lgkmcnt(2)
	v_pk_fma_f32 v[38:39], v[22:23], v[42:43], v[38:39]
	v_pk_fma_f32 v[36:37], v[20:21], v[40:41], v[36:37]
	v_cndmask_b32_e64 v32, v33, v35, s[6:7]
	s_waitcnt lgkmcnt(1)
	v_pk_fma_f32 v[38:39], v[26:27], v[46:47], v[38:39]
	v_pk_fma_f32 v[36:37], v[24:25], v[44:45], v[36:37]
	v_mfma_f32_32x32x2_f32 v[0:15], v198, v32, v[0:15]
	s_waitcnt lgkmcnt(0)
	v_fma_f32 v38, v30, v164, v38
	v_fma_f32 v39, v31, v165, v39
	v_fma_f32 v36, v28, v162, v36
	v_fma_f32 v37, v29, v163, v37
	v_add_f32_e32 v34, v166, v167
	v_mfma_f32_32x32x2_f32 v[16:31], v199, v32, v[16:31]
	v_add_f32_e32 v32, v168, v169
	v_add_f32_e32 v32, v32, v34
	v_add_f32_e32 v34, v36, v37
	v_add_f32_e32 v36, v38, v39
	v_add_f32_e32 v34, v34, v36
	v_add_f32_e32 v32, v32, v34
	v_mov_b32_e32 v34, v32
	s_nop 1
	v_permlane32_swap_b32_e32 v32, v34
	s_and_saveexec_b64 s[28:29], s[6:7]
	s_cbranch_execz .LBB0_503
	s_add_i32 s39, s30, 39
	s_and_b64 s[34:35], s[8:9], exec
	s_cselect_b32 s34, s26, s39
	s_ashr_i32 s35, s34, 31
	s_waitcnt lgkmcnt(0)
	v_mul_f32_e32 v35, v35, v170
	v_mul_f32_e32 v33, v33, v171
	v_pk_add_f32 v[32:33], v[32:33], v[34:35]
	s_nop 0
	v_add_f32_e32 v34, v32, v33
	v_lshl_add_u64 v[32:33], v[66:67], 0, s[34:35]
	v_lshlrev_b64 v[32:33], 11, v[32:33]
	v_lshl_add_u64 v[32:33], v[68:69], 0, v[32:33]
	global_store_dword v[32:33], v34, off
.LBB0_503:
	s_or_b64 exec, exec, s[28:29]
	ds_read_b128 v[32:35], v59 offset:1280
	ds_read_b128 v[36:39], v59 offset:1312
	ds_read_b128 v[162:165], v59 offset:2048
	ds_read_b128 v[166:169], v59 offset:2080
	ds_read_b128 v[40:43], v59 offset:1344
	ds_read_b128 v[44:47], v59 offset:1376
	ds_read_b128 v[170:173], v59 offset:2112
	ds_read_b128 v[174:177], v59 offset:2144
	ds_read_b128 v[178:181], v59 offset:1408
	ds_read_b128 v[182:185], v59 offset:1440
	ds_read_b128 v[186:189], v59 offset:2176
	ds_read_b128 v[190:193], v59 offset:2208
	ds_read_b128 v[194:197], v59 offset:1472
	ds_read_b128 v[198:201], v59 offset:1504
	ds_read_b128 v[202:205], v59 offset:2240
	ds_read_b128 v[206:209], v59 offset:2272
	s_waitcnt lgkmcnt(14)
	v_pk_fma_f32 v[34:35], v[2:3], v[34:35], 0 op_sel_hi:[1,1,0]
	v_pk_fma_f32 v[32:33], v[0:1], v[32:33], 0 op_sel_hi:[1,1,0]
	s_waitcnt lgkmcnt(7)
	v_pk_fma_f32 v[180:181], v[18:19], v[180:181], 0 op_sel_hi:[1,1,0]
	v_pk_fma_f32 v[178:179], v[16:17], v[178:179], 0 op_sel_hi:[1,1,0]
	v_pk_fma_f32 v[34:35], v[6:7], v[38:39], v[34:35]
	v_pk_fma_f32 v[32:33], v[4:5], v[36:37], v[32:33]
	s_waitcnt lgkmcnt(6)
	v_pk_fma_f32 v[36:37], v[22:23], v[184:185], v[180:181]
	v_pk_fma_f32 v[38:39], v[20:21], v[182:183], v[178:179]
	v_pk_fma_f32 v[32:33], v[8:9], v[40:41], v[32:33]
	v_pk_fma_f32 v[34:35], v[10:11], v[42:43], v[34:35]
	s_waitcnt lgkmcnt(3)
	v_pk_fma_f32 v[38:39], v[24:25], v[194:195], v[38:39]
	v_pk_fma_f32 v[36:37], v[26:27], v[196:197], v[36:37]
	v_pk_fma_f32 v[34:35], v[14:15], v[46:47], v[34:35]
	v_pk_fma_f32 v[32:33], v[12:13], v[44:45], v[32:33]
	s_waitcnt lgkmcnt(2)
	v_pk_fma_f32 v[36:37], v[30:31], v[200:201], v[36:37]
	v_pk_fma_f32 v[38:39], v[28:29], v[198:199], v[38:39]
	v_add_f32_e32 v32, v32, v33
	v_add_f32_e32 v33, v34, v35
	v_add_u32_e32 v159, 0x400, v61
	v_add_f32_e32 v32, v32, v33
	v_add_f32_e32 v33, v38, v39
	v_add_f32_e32 v34, v36, v37
	ds_read2_b32 v[210:211], v159 offset0:128 offset1:160
	ds_read_b32 v159, v158 offset:2304
	ds_read_b64 v[194:195], v50 offset:20744
	v_add_f32_e32 v33, v33, v34
	v_add_f32_e32 v32, v32, v33
	v_mov_b32_e32 v33, v32
	s_nop 1
	v_permlane32_swap_b32_e32 v32, v33
	v_add_f32_e32 v161, v32, v33
	s_waitcnt lgkmcnt(0)
	v_cndmask_b32_e64 v178, v159, v161, s[6:7]
	v_pk_fma_f32 v[164:165], v[2:3], v[164:165], 0 op_sel_hi:[1,1,0]
	v_pk_fma_f32 v[162:163], v[0:1], v[162:163], 0 op_sel_hi:[1,1,0]
	v_mfma_f32_32x32x2_f32 v[32:47], v211, v178, v[16:31]
	v_fma_f32 v18, v18, v188, 0
	v_fma_f32 v19, v19, v189, 0
	v_fma_f32 v16, v16, v186, 0
	v_fma_f32 v17, v17, v187, 0
	v_fma_f32 v164, v6, v168, v164
	v_fma_f32 v165, v7, v169, v165
	v_fma_f32 v162, v4, v166, v162
	v_fma_f32 v163, v5, v167, v163
	v_fma_f32 v18, v22, v192, v18
	v_fma_f32 v19, v23, v193, v19
	v_fma_f32 v16, v20, v190, v16
	v_fma_f32 v17, v21, v191, v17
	v_fma_f32 v20, v8, v170, v162
	v_fma_f32 v21, v9, v171, v163
	v_pk_fma_f32 v[22:23], v[10:11], v[172:173], v[164:165]
	v_pk_fma_f32 v[20:21], v[12:13], v[174:175], v[20:21]
	v_pk_fma_f32 v[22:23], v[14:15], v[176:177], v[22:23]
	v_pk_fma_f32 v[16:17], v[24:25], v[202:203], v[16:17]
	v_pk_fma_f32 v[18:19], v[26:27], v[204:205], v[18:19]
	v_pk_fma_f32 v[16:17], v[28:29], v[206:207], v[16:17]
	v_pk_fma_f32 v[18:19], v[30:31], v[208:209], v[18:19]
	v_add_f32_e32 v20, v20, v21
	v_mfma_f32_32x32x2_f32 v[0:15], v210, v178, v[0:15]
	v_add_f32_e32 v21, v22, v23
	v_add_f32_e32 v16, v16, v17
	v_add_f32_e32 v17, v18, v19
	v_add_f32_e32 v20, v20, v21
	v_add_f32_e32 v16, v16, v17
	v_add_f32_e32 v16, v20, v16
	v_mov_b32_e32 v18, v16
	s_nop 1
	v_permlane32_swap_b32_e32 v16, v18
	s_and_saveexec_b64 s[28:29], s[6:7]
	s_cbranch_execz .LBB0_505
	s_add_i32 s39, s26, 1
	s_add_i32 s41, s30, 38
	s_and_b64 s[34:35], s[8:9], exec
	s_cselect_b32 s34, s39, s41
	s_waitcnt lgkmcnt(0)
	v_mul_f32_e32 v19, v161, v194
	v_mul_f32_e32 v17, v159, v195
	v_pk_add_f32 v[16:17], v[16:17], v[18:19]
	s_ashr_i32 s35, s34, 31
	v_add_f32_e32 v18, v16, v17
	v_lshl_add_u64 v[16:17], v[66:67], 0, s[34:35]
	v_lshlrev_b64 v[16:17], 11, v[16:17]
	v_lshl_add_u64 v[16:17], v[68:69], 0, v[16:17]
	global_store_dword v[16:17], v18, off
.LBB0_505:
	s_or_b64 exec, exec, s[28:29]
	ds_read_b128 v[18:21], v59 offset:2560
	ds_read_b128 v[22:25], v59 offset:2592
	ds_read_b128 v[26:29], v59 offset:3328
	ds_read_b128 v[162:165], v59 offset:3360
	ds_read_b128 v[166:169], v59 offset:2624
	ds_read_b128 v[170:173], v59 offset:2656
	ds_read_b128 v[174:177], v59 offset:3392
	ds_read_b128 v[178:181], v59 offset:3424
	ds_read_b128 v[182:185], v59 offset:2688
	ds_read_b128 v[186:189], v59 offset:2720
	ds_read_b128 v[190:193], v59 offset:2752
	ds_read_b128 v[194:197], v59 offset:2784
	s_waitcnt lgkmcnt(11)
	v_pk_fma_f32 v[20:21], v[2:3], v[20:21], 0 op_sel_hi:[1,1,0]
	v_pk_fma_f32 v[18:19], v[0:1], v[18:19], 0 op_sel_hi:[1,1,0]
	s_waitcnt lgkmcnt(3)
	v_pk_fma_f32 v[30:31], v[34:35], v[184:185], 0 op_sel_hi:[1,1,0]
	v_pk_fma_f32 v[182:183], v[32:33], v[182:183], 0 op_sel_hi:[1,1,0]
	v_pk_fma_f32 v[20:21], v[6:7], v[24:25], v[20:21]
	v_pk_fma_f32 v[18:19], v[4:5], v[22:23], v[18:19]
	s_waitcnt lgkmcnt(2)
	v_pk_fma_f32 v[22:23], v[38:39], v[188:189], v[30:31]
	v_pk_fma_f32 v[24:25], v[36:37], v[186:187], v[182:183]
	v_pk_fma_f32 v[18:19], v[8:9], v[166:167], v[18:19]
	v_pk_fma_f32 v[20:21], v[10:11], v[168:169], v[20:21]
	s_waitcnt lgkmcnt(1)
	v_pk_fma_f32 v[22:23], v[42:43], v[192:193], v[22:23]
	v_add_u32_e32 v16, 0x800, v61
	v_pk_fma_f32 v[24:25], v[40:41], v[190:191], v[24:25]
	v_pk_fma_f32 v[20:21], v[14:15], v[172:173], v[20:21]
	v_pk_fma_f32 v[18:19], v[12:13], v[170:171], v[18:19]
	s_waitcnt lgkmcnt(0)
	v_pk_fma_f32 v[22:23], v[46:47], v[196:197], v[22:23]
	ds_read2_b32 v[198:199], v16 offset0:192 offset1:224
	ds_read_b32 v17, v158 offset:3584
	ds_read_b64 v[170:171], v50 offset:20752
	v_pk_fma_f32 v[24:25], v[44:45], v[194:195], v[24:25]
	v_add_f32_e32 v16, v18, v19
	v_add_f32_e32 v18, v20, v21
	v_add_f32_e32 v19, v22, v23
	v_pk_fma_f32 v[20:21], v[2:3], v[28:29], 0 op_sel_hi:[1,1,0]
	v_pk_fma_f32 v[22:23], v[0:1], v[26:27], 0 op_sel_hi:[1,1,0]
	v_add_f32_e32 v16, v16, v18
	v_add_f32_e32 v18, v24, v25
	v_pk_fma_f32 v[20:21], v[6:7], v[164:165], v[20:21]
	v_pk_fma_f32 v[22:23], v[4:5], v[162:163], v[22:23]
	v_add_f32_e32 v18, v18, v19
	v_pk_fma_f32 v[22:23], v[8:9], v[174:175], v[22:23]
	v_pk_fma_f32 v[20:21], v[10:11], v[176:177], v[20:21]
	v_add_f32_e32 v16, v16, v18
	v_pk_fma_f32 v[166:167], v[14:15], v[180:181], v[20:21]
	v_pk_fma_f32 v[168:169], v[12:13], v[178:179], v[22:23]
	ds_read_b128 v[20:23], v59 offset:3456
	ds_read_b128 v[24:27], v59 offset:3488
	ds_read_b128 v[28:31], v59 offset:3520
	ds_read_b128 v[162:165], v59 offset:3552
	v_mov_b32_e32 v18, v16
	s_nop 1
	v_permlane32_swap_b32_e32 v16, v18
	s_waitcnt lgkmcnt(3)
	v_pk_fma_f32 v[22:23], v[34:35], v[22:23], 0 op_sel_hi:[1,1,0]
	v_pk_fma_f32 v[20:21], v[32:33], v[20:21], 0 op_sel_hi:[1,1,0]
	v_add_f32_e32 v19, v16, v18
	s_waitcnt lgkmcnt(2)
	v_pk_fma_f32 v[22:23], v[38:39], v[26:27], v[22:23]
	v_pk_fma_f32 v[20:21], v[36:37], v[24:25], v[20:21]
	v_cndmask_b32_e64 v16, v17, v19, s[6:7]
	s_waitcnt lgkmcnt(1)
	v_pk_fma_f32 v[20:21], v[40:41], v[28:29], v[20:21]
	v_pk_fma_f32 v[22:23], v[42:43], v[30:31], v[22:23]
	v_mfma_f32_32x32x2_f32 v[0:15], v198, v16, v[0:15]
	s_waitcnt lgkmcnt(0)
	v_fma_f32 v22, v46, v164, v22
	v_fma_f32 v23, v47, v165, v23
	v_fma_f32 v20, v44, v162, v20
	v_fma_f32 v21, v45, v163, v21
	v_add_f32_e32 v18, v166, v167
	v_mfma_f32_32x32x2_f32 v[32:47], v199, v16, v[32:47]
	v_add_f32_e32 v16, v168, v169
	v_add_f32_e32 v16, v16, v18
	v_add_f32_e32 v18, v20, v21
	v_add_f32_e32 v20, v22, v23
	v_add_f32_e32 v18, v18, v20
	v_add_f32_e32 v16, v16, v18
	v_mov_b32_e32 v18, v16
	s_nop 1
	v_permlane32_swap_b32_e32 v16, v18
	s_and_saveexec_b64 s[28:29], s[6:7]
	s_cbranch_execz .LBB0_507
	s_add_i32 s39, s26, 2
	s_add_i32 s41, s30, 37
	s_and_b64 s[34:35], s[8:9], exec
	s_cselect_b32 s34, s39, s41
	s_waitcnt lgkmcnt(0)
	v_mul_f32_e32 v19, v19, v170
	v_mul_f32_e32 v17, v17, v171
	v_pk_add_f32 v[16:17], v[16:17], v[18:19]
	s_ashr_i32 s35, s34, 31
	v_add_f32_e32 v18, v16, v17
	v_lshl_add_u64 v[16:17], v[66:67], 0, s[34:35]
	v_lshlrev_b64 v[16:17], 11, v[16:17]
	v_lshl_add_u64 v[16:17], v[68:69], 0, v[16:17]
	global_store_dword v[16:17], v18, off
.LBB0_507:
	s_or_b64 exec, exec, s[28:29]
	ds_read_b128 v[16:19], v59 offset:3840
	ds_read_b128 v[20:23], v59 offset:3872
	ds_read_b128 v[162:165], v59 offset:4608
	ds_read_b128 v[166:169], v59 offset:4640
	ds_read_b128 v[24:27], v59 offset:3904
	ds_read_b128 v[28:31], v59 offset:3936
	ds_read_b128 v[170:173], v59 offset:4672
	ds_read_b128 v[174:177], v59 offset:4704
	ds_read_b128 v[178:181], v59 offset:3968
	ds_read_b128 v[182:185], v59 offset:4000
	ds_read_b128 v[186:189], v59 offset:4736
	ds_read_b128 v[190:193], v59 offset:4768
	ds_read_b128 v[194:197], v59 offset:4032
	ds_read_b128 v[198:201], v59 offset:4064
	ds_read_b128 v[202:205], v59 offset:4800
	ds_read_b128 v[206:209], v59 offset:4832
	s_waitcnt lgkmcnt(14)
	v_pk_fma_f32 v[18:19], v[2:3], v[18:19], 0 op_sel_hi:[1,1,0]
	v_pk_fma_f32 v[16:17], v[0:1], v[16:17], 0 op_sel_hi:[1,1,0]
	s_waitcnt lgkmcnt(7)
	v_pk_fma_f32 v[180:181], v[34:35], v[180:181], 0 op_sel_hi:[1,1,0]
	v_pk_fma_f32 v[178:179], v[32:33], v[178:179], 0 op_sel_hi:[1,1,0]
	v_pk_fma_f32 v[18:19], v[6:7], v[22:23], v[18:19]
	v_pk_fma_f32 v[16:17], v[4:5], v[20:21], v[16:17]
	s_waitcnt lgkmcnt(6)
	v_pk_fma_f32 v[20:21], v[38:39], v[184:185], v[180:181]
	v_pk_fma_f32 v[22:23], v[36:37], v[182:183], v[178:179]
	v_pk_fma_f32 v[16:17], v[8:9], v[24:25], v[16:17]
	v_pk_fma_f32 v[18:19], v[10:11], v[26:27], v[18:19]
	s_waitcnt lgkmcnt(3)
	v_pk_fma_f32 v[22:23], v[40:41], v[194:195], v[22:23]
	v_pk_fma_f32 v[20:21], v[42:43], v[196:197], v[20:21]
	v_pk_fma_f32 v[18:19], v[14:15], v[30:31], v[18:19]
	v_pk_fma_f32 v[16:17], v[12:13], v[28:29], v[16:17]
	s_waitcnt lgkmcnt(2)
	v_pk_fma_f32 v[20:21], v[46:47], v[200:201], v[20:21]
	v_pk_fma_f32 v[22:23], v[44:45], v[198:199], v[22:23]
	v_add_f32_e32 v16, v16, v17
	v_add_f32_e32 v17, v18, v19
	v_add_u32_e32 v159, 0x1000, v61
	v_add_f32_e32 v16, v16, v17
	v_add_f32_e32 v17, v22, v23
	v_add_f32_e32 v18, v20, v21
	ds_read2_b32 v[210:211], v159 offset1:32
	ds_read_b32 v159, v158 offset:4864
	ds_read_b64 v[194:195], v50 offset:20760
	v_add_f32_e32 v17, v17, v18
	v_add_f32_e32 v16, v16, v17
	v_mov_b32_e32 v17, v16
	s_nop 1
	v_permlane32_swap_b32_e32 v16, v17
	v_add_f32_e32 v161, v16, v17
	s_waitcnt lgkmcnt(0)
	v_cndmask_b32_e64 v178, v159, v161, s[6:7]
	v_pk_fma_f32 v[164:165], v[2:3], v[164:165], 0 op_sel_hi:[1,1,0]
	v_pk_fma_f32 v[162:163], v[0:1], v[162:163], 0 op_sel_hi:[1,1,0]
	v_mfma_f32_32x32x2_f32 v[16:31], v211, v178, v[32:47]
	v_fma_f32 v34, v34, v188, 0
	v_fma_f32 v35, v35, v189, 0
	v_fma_f32 v32, v32, v186, 0
	v_fma_f32 v33, v33, v187, 0
	v_fma_f32 v164, v6, v168, v164
	v_fma_f32 v165, v7, v169, v165
	v_fma_f32 v162, v4, v166, v162
	v_fma_f32 v163, v5, v167, v163
	v_fma_f32 v34, v38, v192, v34
	v_fma_f32 v35, v39, v193, v35
	v_fma_f32 v32, v36, v190, v32
	v_fma_f32 v33, v37, v191, v33
	v_fma_f32 v36, v8, v170, v162
	v_fma_f32 v37, v9, v171, v163
	v_pk_fma_f32 v[38:39], v[10:11], v[172:173], v[164:165]
	v_pk_fma_f32 v[36:37], v[12:13], v[174:175], v[36:37]
	v_pk_fma_f32 v[38:39], v[14:15], v[176:177], v[38:39]
	v_pk_fma_f32 v[32:33], v[40:41], v[202:203], v[32:33]
	v_pk_fma_f32 v[34:35], v[42:43], v[204:205], v[34:35]
	v_pk_fma_f32 v[32:33], v[44:45], v[206:207], v[32:33]
	v_pk_fma_f32 v[34:35], v[46:47], v[208:209], v[34:35]
	v_add_f32_e32 v36, v36, v37
	v_mfma_f32_32x32x2_f32 v[0:15], v210, v178, v[0:15]
	v_add_f32_e32 v37, v38, v39
	v_add_f32_e32 v32, v32, v33
	v_add_f32_e32 v33, v34, v35
	v_add_f32_e32 v36, v36, v37
	v_add_f32_e32 v32, v32, v33
	v_add_f32_e32 v32, v36, v32
	v_mov_b32_e32 v34, v32
	s_nop 1
	v_permlane32_swap_b32_e32 v32, v34
	s_and_saveexec_b64 s[28:29], s[6:7]
	s_cbranch_execz .LBB0_509
	s_add_i32 s39, s26, 3
	s_add_i32 s41, s30, 36
	s_and_b64 s[34:35], s[8:9], exec
	s_cselect_b32 s34, s39, s41
	s_waitcnt lgkmcnt(0)
	v_mul_f32_e32 v35, v161, v194
	v_mul_f32_e32 v33, v159, v195
	v_pk_add_f32 v[32:33], v[32:33], v[34:35]
	s_ashr_i32 s35, s34, 31
	v_add_f32_e32 v34, v32, v33
	v_lshl_add_u64 v[32:33], v[66:67], 0, s[34:35]
	v_lshlrev_b64 v[32:33], 11, v[32:33]
	v_lshl_add_u64 v[32:33], v[68:69], 0, v[32:33]
	global_store_dword v[32:33], v34, off
.LBB0_509:
	s_or_b64 exec, exec, s[28:29]
	ds_read_b128 v[34:37], v59 offset:5120
	ds_read_b128 v[38:41], v59 offset:5152
	ds_read_b128 v[42:45], v59 offset:5888
	ds_read_b128 v[162:165], v59 offset:5920
	ds_read_b128 v[166:169], v59 offset:5184
	ds_read_b128 v[170:173], v59 offset:5216
	ds_read_b128 v[174:177], v59 offset:5952
	ds_read_b128 v[178:181], v59 offset:5984
	ds_read_b128 v[182:185], v59 offset:5248
	ds_read_b128 v[186:189], v59 offset:5280
	ds_read_b128 v[190:193], v59 offset:5312
	ds_read_b128 v[194:197], v59 offset:5344
	s_waitcnt lgkmcnt(11)
	v_pk_fma_f32 v[36:37], v[2:3], v[36:37], 0 op_sel_hi:[1,1,0]
	v_pk_fma_f32 v[34:35], v[0:1], v[34:35], 0 op_sel_hi:[1,1,0]
	s_waitcnt lgkmcnt(3)
	v_pk_fma_f32 v[46:47], v[18:19], v[184:185], 0 op_sel_hi:[1,1,0]
	v_pk_fma_f32 v[182:183], v[16:17], v[182:183], 0 op_sel_hi:[1,1,0]
	v_pk_fma_f32 v[36:37], v[6:7], v[40:41], v[36:37]
	v_pk_fma_f32 v[34:35], v[4:5], v[38:39], v[34:35]
	s_waitcnt lgkmcnt(2)
	v_pk_fma_f32 v[38:39], v[22:23], v[188:189], v[46:47]
	v_pk_fma_f32 v[40:41], v[20:21], v[186:187], v[182:183]
	v_pk_fma_f32 v[34:35], v[8:9], v[166:167], v[34:35]
	v_pk_fma_f32 v[36:37], v[10:11], v[168:169], v[36:37]
	s_waitcnt lgkmcnt(1)
	v_pk_fma_f32 v[38:39], v[26:27], v[192:193], v[38:39]
	v_add_u32_e32 v32, 0x1400, v61
	v_pk_fma_f32 v[40:41], v[24:25], v[190:191], v[40:41]
	v_pk_fma_f32 v[36:37], v[14:15], v[172:173], v[36:37]
	v_pk_fma_f32 v[34:35], v[12:13], v[170:171], v[34:35]
	s_waitcnt lgkmcnt(0)
	v_pk_fma_f32 v[38:39], v[30:31], v[196:197], v[38:39]
	ds_read2_b32 v[198:199], v32 offset0:64 offset1:96
	ds_read_b32 v33, v158 offset:6144
	ds_read_b64 v[170:171], v50 offset:20768
	v_pk_fma_f32 v[40:41], v[28:29], v[194:195], v[40:41]
	v_add_f32_e32 v32, v34, v35
	v_add_f32_e32 v34, v36, v37
	v_add_f32_e32 v35, v38, v39
	v_pk_fma_f32 v[36:37], v[2:3], v[44:45], 0 op_sel_hi:[1,1,0]
	v_pk_fma_f32 v[38:39], v[0:1], v[42:43], 0 op_sel_hi:[1,1,0]
	v_add_f32_e32 v32, v32, v34
	v_add_f32_e32 v34, v40, v41
	v_pk_fma_f32 v[36:37], v[6:7], v[164:165], v[36:37]
	v_pk_fma_f32 v[38:39], v[4:5], v[162:163], v[38:39]
	v_add_f32_e32 v34, v34, v35
	v_pk_fma_f32 v[38:39], v[8:9], v[174:175], v[38:39]
	v_pk_fma_f32 v[36:37], v[10:11], v[176:177], v[36:37]
	v_add_f32_e32 v32, v32, v34
	v_pk_fma_f32 v[166:167], v[14:15], v[180:181], v[36:37]
	v_pk_fma_f32 v[168:169], v[12:13], v[178:179], v[38:39]
	ds_read_b128 v[36:39], v59 offset:6016
	ds_read_b128 v[40:43], v59 offset:6048
	ds_read_b128 v[44:47], v59 offset:6080
	ds_read_b128 v[162:165], v59 offset:6112
	v_mov_b32_e32 v34, v32
	s_nop 1
	v_permlane32_swap_b32_e32 v32, v34
	s_waitcnt lgkmcnt(3)
	v_pk_fma_f32 v[38:39], v[18:19], v[38:39], 0 op_sel_hi:[1,1,0]
	v_pk_fma_f32 v[36:37], v[16:17], v[36:37], 0 op_sel_hi:[1,1,0]
	v_add_f32_e32 v35, v32, v34
	s_waitcnt lgkmcnt(2)
	v_pk_fma_f32 v[38:39], v[22:23], v[42:43], v[38:39]
	v_pk_fma_f32 v[36:37], v[20:21], v[40:41], v[36:37]
	v_cndmask_b32_e64 v32, v33, v35, s[6:7]
	s_waitcnt lgkmcnt(1)
	v_pk_fma_f32 v[36:37], v[24:25], v[44:45], v[36:37]
	v_pk_fma_f32 v[38:39], v[26:27], v[46:47], v[38:39]
	v_mfma_f32_32x32x2_f32 v[0:15], v198, v32, v[0:15]
	s_waitcnt lgkmcnt(0)
	v_fma_f32 v38, v30, v164, v38
	v_fma_f32 v39, v31, v165, v39
	v_fma_f32 v36, v28, v162, v36
	v_fma_f32 v37, v29, v163, v37
	v_add_f32_e32 v34, v166, v167
	v_mfma_f32_32x32x2_f32 v[16:31], v199, v32, v[16:31]
	v_add_f32_e32 v32, v168, v169
	v_add_f32_e32 v32, v32, v34
	v_add_f32_e32 v34, v36, v37
	v_add_f32_e32 v36, v38, v39
	v_add_f32_e32 v34, v34, v36
	v_add_f32_e32 v32, v32, v34
	v_mov_b32_e32 v34, v32
	s_nop 1
	v_permlane32_swap_b32_e32 v32, v34
	s_and_saveexec_b64 s[28:29], s[6:7]
	s_cbranch_execz .LBB0_511
	s_add_i32 s39, s26, 4
	s_add_i32 s41, s30, 35
	s_and_b64 s[34:35], s[8:9], exec
	s_cselect_b32 s34, s39, s41
	s_waitcnt lgkmcnt(0)
	v_mul_f32_e32 v35, v35, v170
	v_mul_f32_e32 v33, v33, v171
	v_pk_add_f32 v[32:33], v[32:33], v[34:35]
	s_ashr_i32 s35, s34, 31
	v_add_f32_e32 v34, v32, v33
	v_lshl_add_u64 v[32:33], v[66:67], 0, s[34:35]
	v_lshlrev_b64 v[32:33], 11, v[32:33]
	v_lshl_add_u64 v[32:33], v[68:69], 0, v[32:33]
	global_store_dword v[32:33], v34, off
.LBB0_511:
	s_or_b64 exec, exec, s[28:29]
	ds_read_b128 v[32:35], v59 offset:6400
	ds_read_b128 v[36:39], v59 offset:6432
	ds_read_b128 v[162:165], v59 offset:7168
	ds_read_b128 v[166:169], v59 offset:7200
	ds_read_b128 v[40:43], v59 offset:6464
	ds_read_b128 v[44:47], v59 offset:6496
	ds_read_b128 v[170:173], v59 offset:7232
	ds_read_b128 v[174:177], v59 offset:7264
	ds_read_b128 v[178:181], v59 offset:6528
	ds_read_b128 v[182:185], v59 offset:6560
	ds_read_b128 v[186:189], v59 offset:7296
	ds_read_b128 v[190:193], v59 offset:7328
	ds_read_b128 v[194:197], v59 offset:6592
	ds_read_b128 v[198:201], v59 offset:6624
	ds_read_b128 v[202:205], v59 offset:7360
	ds_read_b128 v[206:209], v59 offset:7392
	s_waitcnt lgkmcnt(14)
	v_pk_fma_f32 v[34:35], v[2:3], v[34:35], 0 op_sel_hi:[1,1,0]
	v_pk_fma_f32 v[32:33], v[0:1], v[32:33], 0 op_sel_hi:[1,1,0]
	s_waitcnt lgkmcnt(7)
	v_pk_fma_f32 v[180:181], v[18:19], v[180:181], 0 op_sel_hi:[1,1,0]
	v_pk_fma_f32 v[178:179], v[16:17], v[178:179], 0 op_sel_hi:[1,1,0]
	v_pk_fma_f32 v[34:35], v[6:7], v[38:39], v[34:35]
	v_pk_fma_f32 v[32:33], v[4:5], v[36:37], v[32:33]
	s_waitcnt lgkmcnt(6)
	v_pk_fma_f32 v[36:37], v[22:23], v[184:185], v[180:181]
	v_pk_fma_f32 v[38:39], v[20:21], v[182:183], v[178:179]
	v_pk_fma_f32 v[32:33], v[8:9], v[40:41], v[32:33]
	v_pk_fma_f32 v[34:35], v[10:11], v[42:43], v[34:35]
	s_waitcnt lgkmcnt(3)
	v_pk_fma_f32 v[38:39], v[24:25], v[194:195], v[38:39]
	v_pk_fma_f32 v[36:37], v[26:27], v[196:197], v[36:37]
	v_pk_fma_f32 v[34:35], v[14:15], v[46:47], v[34:35]
	v_pk_fma_f32 v[32:33], v[12:13], v[44:45], v[32:33]
	s_waitcnt lgkmcnt(2)
	v_pk_fma_f32 v[36:37], v[30:31], v[200:201], v[36:37]
	v_pk_fma_f32 v[38:39], v[28:29], v[198:199], v[38:39]
	v_add_f32_e32 v32, v32, v33
	v_add_f32_e32 v33, v34, v35
	v_add_u32_e32 v159, 0x1800, v61
	v_add_f32_e32 v32, v32, v33
	v_add_f32_e32 v33, v38, v39
	v_add_f32_e32 v34, v36, v37
	ds_read2_b32 v[210:211], v159 offset0:128 offset1:160
	ds_read_b32 v159, v158 offset:7424
	ds_read_b64 v[194:195], v50 offset:20776
	v_add_f32_e32 v33, v33, v34
	v_add_f32_e32 v32, v32, v33
	v_mov_b32_e32 v33, v32
	s_nop 1
	v_permlane32_swap_b32_e32 v32, v33
	v_add_f32_e32 v161, v32, v33
	s_waitcnt lgkmcnt(0)
	v_cndmask_b32_e64 v178, v159, v161, s[6:7]
	v_pk_fma_f32 v[164:165], v[2:3], v[164:165], 0 op_sel_hi:[1,1,0]
	v_pk_fma_f32 v[162:163], v[0:1], v[162:163], 0 op_sel_hi:[1,1,0]
	v_mfma_f32_32x32x2_f32 v[32:47], v211, v178, v[16:31]
	v_fma_f32 v18, v18, v188, 0
	v_fma_f32 v19, v19, v189, 0
	v_fma_f32 v16, v16, v186, 0
	v_fma_f32 v17, v17, v187, 0
	v_fma_f32 v164, v6, v168, v164
	v_fma_f32 v165, v7, v169, v165
	v_fma_f32 v162, v4, v166, v162
	v_fma_f32 v163, v5, v167, v163
	v_fma_f32 v18, v22, v192, v18
	v_fma_f32 v19, v23, v193, v19
	v_fma_f32 v16, v20, v190, v16
	v_fma_f32 v17, v21, v191, v17
	v_fma_f32 v20, v8, v170, v162
	v_fma_f32 v21, v9, v171, v163
	v_pk_fma_f32 v[22:23], v[10:11], v[172:173], v[164:165]
	v_pk_fma_f32 v[20:21], v[12:13], v[174:175], v[20:21]
	v_pk_fma_f32 v[22:23], v[14:15], v[176:177], v[22:23]
	v_pk_fma_f32 v[16:17], v[24:25], v[202:203], v[16:17]
	v_pk_fma_f32 v[18:19], v[26:27], v[204:205], v[18:19]
	v_pk_fma_f32 v[16:17], v[28:29], v[206:207], v[16:17]
	v_pk_fma_f32 v[18:19], v[30:31], v[208:209], v[18:19]
	v_add_f32_e32 v20, v20, v21
	v_mfma_f32_32x32x2_f32 v[0:15], v210, v178, v[0:15]
	v_add_f32_e32 v21, v22, v23
	v_add_f32_e32 v16, v16, v17
	v_add_f32_e32 v17, v18, v19
	v_add_f32_e32 v20, v20, v21
	v_add_f32_e32 v16, v16, v17
	v_add_f32_e32 v16, v20, v16
	v_mov_b32_e32 v18, v16
	s_nop 1
	v_permlane32_swap_b32_e32 v16, v18
	s_and_saveexec_b64 s[28:29], s[6:7]
	s_cbranch_execz .LBB0_513
	s_add_i32 s39, s26, 5
	s_add_i32 s41, s30, 34
	s_and_b64 s[34:35], s[8:9], exec
	s_cselect_b32 s34, s39, s41
	s_waitcnt lgkmcnt(0)
	v_mul_f32_e32 v19, v161, v194
	v_mul_f32_e32 v17, v159, v195
	v_pk_add_f32 v[16:17], v[16:17], v[18:19]
	s_ashr_i32 s35, s34, 31
	v_add_f32_e32 v18, v16, v17
	v_lshl_add_u64 v[16:17], v[66:67], 0, s[34:35]
	v_lshlrev_b64 v[16:17], 11, v[16:17]
	v_lshl_add_u64 v[16:17], v[68:69], 0, v[16:17]
	global_store_dword v[16:17], v18, off
.LBB0_513:
	s_or_b64 exec, exec, s[28:29]
	ds_read_b128 v[18:21], v59 offset:7680
	ds_read_b128 v[22:25], v59 offset:7712
	ds_read_b128 v[26:29], v59 offset:8448
	ds_read_b128 v[162:165], v59 offset:8480
	ds_read_b128 v[166:169], v59 offset:7744
	ds_read_b128 v[170:173], v59 offset:7776
	ds_read_b128 v[174:177], v59 offset:8512
	ds_read_b128 v[178:181], v59 offset:8544
	ds_read_b128 v[182:185], v59 offset:7808
	ds_read_b128 v[186:189], v59 offset:7840
	ds_read_b128 v[190:193], v59 offset:7872
	ds_read_b128 v[194:197], v59 offset:7904
	s_waitcnt lgkmcnt(11)
	v_pk_fma_f32 v[20:21], v[2:3], v[20:21], 0 op_sel_hi:[1,1,0]
	v_pk_fma_f32 v[18:19], v[0:1], v[18:19], 0 op_sel_hi:[1,1,0]
	s_waitcnt lgkmcnt(3)
	v_pk_fma_f32 v[30:31], v[34:35], v[184:185], 0 op_sel_hi:[1,1,0]
	v_pk_fma_f32 v[182:183], v[32:33], v[182:183], 0 op_sel_hi:[1,1,0]
	v_pk_fma_f32 v[20:21], v[6:7], v[24:25], v[20:21]
	v_pk_fma_f32 v[18:19], v[4:5], v[22:23], v[18:19]
	s_waitcnt lgkmcnt(2)
	v_pk_fma_f32 v[22:23], v[38:39], v[188:189], v[30:31]
	v_pk_fma_f32 v[24:25], v[36:37], v[186:187], v[182:183]
	v_pk_fma_f32 v[18:19], v[8:9], v[166:167], v[18:19]
	v_pk_fma_f32 v[20:21], v[10:11], v[168:169], v[20:21]
	s_waitcnt lgkmcnt(1)
	v_pk_fma_f32 v[22:23], v[42:43], v[192:193], v[22:23]
	v_add_u32_e32 v16, 0x1c00, v61
	v_pk_fma_f32 v[24:25], v[40:41], v[190:191], v[24:25]
	v_pk_fma_f32 v[20:21], v[14:15], v[172:173], v[20:21]
	v_pk_fma_f32 v[18:19], v[12:13], v[170:171], v[18:19]
	s_waitcnt lgkmcnt(0)
	v_pk_fma_f32 v[22:23], v[46:47], v[196:197], v[22:23]
	ds_read2_b32 v[198:199], v16 offset0:192 offset1:224
	ds_read_b32 v17, v158 offset:8704
	ds_read_b64 v[170:171], v50 offset:20784
	v_pk_fma_f32 v[24:25], v[44:45], v[194:195], v[24:25]
	v_add_f32_e32 v16, v18, v19
	v_add_f32_e32 v18, v20, v21
	v_add_f32_e32 v19, v22, v23
	v_pk_fma_f32 v[20:21], v[2:3], v[28:29], 0 op_sel_hi:[1,1,0]
	v_pk_fma_f32 v[22:23], v[0:1], v[26:27], 0 op_sel_hi:[1,1,0]
	v_add_f32_e32 v16, v16, v18
	v_add_f32_e32 v18, v24, v25
	v_pk_fma_f32 v[20:21], v[6:7], v[164:165], v[20:21]
	v_pk_fma_f32 v[22:23], v[4:5], v[162:163], v[22:23]
	v_add_f32_e32 v18, v18, v19
	v_pk_fma_f32 v[22:23], v[8:9], v[174:175], v[22:23]
	v_pk_fma_f32 v[20:21], v[10:11], v[176:177], v[20:21]
	v_add_f32_e32 v16, v16, v18
	v_pk_fma_f32 v[166:167], v[14:15], v[180:181], v[20:21]
	v_pk_fma_f32 v[168:169], v[12:13], v[178:179], v[22:23]
	ds_read_b128 v[20:23], v59 offset:8576
	ds_read_b128 v[24:27], v59 offset:8608
	ds_read_b128 v[28:31], v59 offset:8640
	ds_read_b128 v[162:165], v59 offset:8672
	v_mov_b32_e32 v18, v16
	s_nop 1
	v_permlane32_swap_b32_e32 v16, v18
	s_waitcnt lgkmcnt(3)
	v_pk_fma_f32 v[22:23], v[34:35], v[22:23], 0 op_sel_hi:[1,1,0]
	v_pk_fma_f32 v[20:21], v[32:33], v[20:21], 0 op_sel_hi:[1,1,0]
	v_add_f32_e32 v19, v16, v18
	s_waitcnt lgkmcnt(2)
	v_pk_fma_f32 v[22:23], v[38:39], v[26:27], v[22:23]
	v_pk_fma_f32 v[20:21], v[36:37], v[24:25], v[20:21]
	v_cndmask_b32_e64 v16, v17, v19, s[6:7]
	s_waitcnt lgkmcnt(1)
	v_pk_fma_f32 v[20:21], v[40:41], v[28:29], v[20:21]
	v_pk_fma_f32 v[22:23], v[42:43], v[30:31], v[22:23]
	v_mfma_f32_32x32x2_f32 v[0:15], v198, v16, v[0:15]
	s_waitcnt lgkmcnt(0)
	v_fma_f32 v22, v46, v164, v22
	v_fma_f32 v23, v47, v165, v23
	v_fma_f32 v20, v44, v162, v20
	v_fma_f32 v21, v45, v163, v21
	v_add_f32_e32 v18, v166, v167
	v_mfma_f32_32x32x2_f32 v[32:47], v199, v16, v[32:47]
	v_add_f32_e32 v16, v168, v169
	v_add_f32_e32 v16, v16, v18
	v_add_f32_e32 v18, v20, v21
	v_add_f32_e32 v20, v22, v23
	v_add_f32_e32 v18, v18, v20
	v_add_f32_e32 v16, v16, v18
	v_mov_b32_e32 v18, v16
	s_nop 1
	v_permlane32_swap_b32_e32 v16, v18
	s_and_saveexec_b64 s[28:29], s[6:7]
	s_cbranch_execz .LBB0_515
	s_add_i32 s39, s26, 6
	s_add_i32 s41, s30, 33
	s_and_b64 s[34:35], s[8:9], exec
	s_cselect_b32 s34, s39, s41
	s_waitcnt lgkmcnt(0)
	v_mul_f32_e32 v19, v19, v170
	v_mul_f32_e32 v17, v17, v171
	v_pk_add_f32 v[16:17], v[16:17], v[18:19]
	s_ashr_i32 s35, s34, 31
	v_add_f32_e32 v18, v16, v17
	v_lshl_add_u64 v[16:17], v[66:67], 0, s[34:35]
	v_lshlrev_b64 v[16:17], 11, v[16:17]
	v_lshl_add_u64 v[16:17], v[68:69], 0, v[16:17]
	global_store_dword v[16:17], v18, off
.LBB0_515:
	s_or_b64 exec, exec, s[28:29]
	ds_read_b128 v[16:19], v59 offset:8960
	ds_read_b128 v[20:23], v59 offset:8992
	ds_read_b128 v[162:165], v59 offset:9728
	ds_read_b128 v[166:169], v59 offset:9760
	ds_read_b128 v[24:27], v59 offset:9024
	ds_read_b128 v[28:31], v59 offset:9056
	ds_read_b128 v[170:173], v59 offset:9792
	ds_read_b128 v[174:177], v59 offset:9824
	ds_read_b128 v[178:181], v59 offset:9088
	ds_read_b128 v[182:185], v59 offset:9120
	ds_read_b128 v[186:189], v59 offset:9856
	ds_read_b128 v[190:193], v59 offset:9888
	ds_read_b128 v[194:197], v59 offset:9152
	ds_read_b128 v[198:201], v59 offset:9184
	ds_read_b128 v[202:205], v59 offset:9920
	ds_read_b128 v[206:209], v59 offset:9952
	s_waitcnt lgkmcnt(14)
	v_pk_fma_f32 v[18:19], v[2:3], v[18:19], 0 op_sel_hi:[1,1,0]
	v_pk_fma_f32 v[16:17], v[0:1], v[16:17], 0 op_sel_hi:[1,1,0]
	s_waitcnt lgkmcnt(7)
	v_pk_fma_f32 v[180:181], v[34:35], v[180:181], 0 op_sel_hi:[1,1,0]
	v_pk_fma_f32 v[178:179], v[32:33], v[178:179], 0 op_sel_hi:[1,1,0]
	v_pk_fma_f32 v[18:19], v[6:7], v[22:23], v[18:19]
	v_pk_fma_f32 v[16:17], v[4:5], v[20:21], v[16:17]
	s_waitcnt lgkmcnt(6)
	v_pk_fma_f32 v[20:21], v[38:39], v[184:185], v[180:181]
	v_pk_fma_f32 v[22:23], v[36:37], v[182:183], v[178:179]
	v_pk_fma_f32 v[16:17], v[8:9], v[24:25], v[16:17]
	v_pk_fma_f32 v[18:19], v[10:11], v[26:27], v[18:19]
	s_waitcnt lgkmcnt(3)
	v_pk_fma_f32 v[22:23], v[40:41], v[194:195], v[22:23]
	v_pk_fma_f32 v[20:21], v[42:43], v[196:197], v[20:21]
	v_pk_fma_f32 v[18:19], v[14:15], v[30:31], v[18:19]
	v_pk_fma_f32 v[16:17], v[12:13], v[28:29], v[16:17]
	s_waitcnt lgkmcnt(2)
	v_pk_fma_f32 v[20:21], v[46:47], v[200:201], v[20:21]
	v_pk_fma_f32 v[22:23], v[44:45], v[198:199], v[22:23]
	v_add_f32_e32 v16, v16, v17
	v_add_f32_e32 v17, v18, v19
	v_add_u32_e32 v159, 0x2400, v61
	v_add_f32_e32 v16, v16, v17
	v_add_f32_e32 v17, v22, v23
	v_add_f32_e32 v18, v20, v21
	ds_read2_b32 v[210:211], v159 offset1:32
	ds_read_b32 v159, v158 offset:9984
	ds_read_b64 v[194:195], v50 offset:20792
	v_add_f32_e32 v17, v17, v18
	v_add_f32_e32 v16, v16, v17
	v_mov_b32_e32 v17, v16
	s_nop 1
	v_permlane32_swap_b32_e32 v16, v17
	v_add_f32_e32 v161, v16, v17
	s_waitcnt lgkmcnt(0)
	v_cndmask_b32_e64 v178, v159, v161, s[6:7]
	v_pk_fma_f32 v[164:165], v[2:3], v[164:165], 0 op_sel_hi:[1,1,0]
	v_pk_fma_f32 v[162:163], v[0:1], v[162:163], 0 op_sel_hi:[1,1,0]
	v_mfma_f32_32x32x2_f32 v[16:31], v211, v178, v[32:47]
	v_fma_f32 v34, v34, v188, 0
	v_fma_f32 v35, v35, v189, 0
	v_fma_f32 v32, v32, v186, 0
	v_fma_f32 v33, v33, v187, 0
	v_fma_f32 v164, v6, v168, v164
	v_fma_f32 v165, v7, v169, v165
	v_fma_f32 v162, v4, v166, v162
	v_fma_f32 v163, v5, v167, v163
	v_fma_f32 v34, v38, v192, v34
	v_fma_f32 v35, v39, v193, v35
	v_fma_f32 v32, v36, v190, v32
	v_fma_f32 v33, v37, v191, v33
	v_fma_f32 v36, v8, v170, v162
	v_fma_f32 v37, v9, v171, v163
	v_pk_fma_f32 v[38:39], v[10:11], v[172:173], v[164:165]
	v_pk_fma_f32 v[36:37], v[12:13], v[174:175], v[36:37]
	v_pk_fma_f32 v[38:39], v[14:15], v[176:177], v[38:39]
	v_pk_fma_f32 v[32:33], v[40:41], v[202:203], v[32:33]
	v_pk_fma_f32 v[34:35], v[42:43], v[204:205], v[34:35]
	v_pk_fma_f32 v[32:33], v[44:45], v[206:207], v[32:33]
	v_pk_fma_f32 v[34:35], v[46:47], v[208:209], v[34:35]
	v_add_f32_e32 v36, v36, v37
	v_mfma_f32_32x32x2_f32 v[0:15], v210, v178, v[0:15]
	v_add_f32_e32 v37, v38, v39
	v_add_f32_e32 v32, v32, v33
	v_add_f32_e32 v33, v34, v35
	v_add_f32_e32 v36, v36, v37
	v_add_f32_e32 v32, v32, v33
	v_add_f32_e32 v32, v36, v32
	v_mov_b32_e32 v34, v32
	s_nop 1
	v_permlane32_swap_b32_e32 v32, v34
	s_and_saveexec_b64 s[28:29], s[6:7]
	s_cbranch_execz .LBB0_517
	s_add_i32 s39, s26, 7
	s_add_i32 s41, s30, 32
	s_and_b64 s[34:35], s[8:9], exec
	s_cselect_b32 s34, s39, s41
	s_waitcnt lgkmcnt(0)
	v_mul_f32_e32 v35, v161, v194
	v_mul_f32_e32 v33, v159, v195
	v_pk_add_f32 v[32:33], v[32:33], v[34:35]
	s_ashr_i32 s35, s34, 31
	v_add_f32_e32 v34, v32, v33
	v_lshl_add_u64 v[32:33], v[66:67], 0, s[34:35]
	v_lshlrev_b64 v[32:33], 11, v[32:33]
	v_lshl_add_u64 v[32:33], v[68:69], 0, v[32:33]
	global_store_dword v[32:33], v34, off
.LBB0_517:
	s_or_b64 exec, exec, s[28:29]
	ds_read_b128 v[34:37], v59 offset:10240
	ds_read_b128 v[38:41], v59 offset:10272
	ds_read_b128 v[42:45], v59 offset:11008
	ds_read_b128 v[162:165], v59 offset:11040
	ds_read_b128 v[166:169], v59 offset:10304
	ds_read_b128 v[170:173], v59 offset:10336
	ds_read_b128 v[174:177], v59 offset:11072
	ds_read_b128 v[178:181], v59 offset:11104
	ds_read_b128 v[182:185], v59 offset:10368
	ds_read_b128 v[186:189], v59 offset:10400
	ds_read_b128 v[190:193], v59 offset:10432
	ds_read_b128 v[194:197], v59 offset:10464
	s_waitcnt lgkmcnt(11)
	v_pk_fma_f32 v[36:37], v[2:3], v[36:37], 0 op_sel_hi:[1,1,0]
	v_pk_fma_f32 v[34:35], v[0:1], v[34:35], 0 op_sel_hi:[1,1,0]
	s_waitcnt lgkmcnt(3)
	v_pk_fma_f32 v[46:47], v[18:19], v[184:185], 0 op_sel_hi:[1,1,0]
	v_pk_fma_f32 v[182:183], v[16:17], v[182:183], 0 op_sel_hi:[1,1,0]
	v_pk_fma_f32 v[36:37], v[6:7], v[40:41], v[36:37]
	v_pk_fma_f32 v[34:35], v[4:5], v[38:39], v[34:35]
	s_waitcnt lgkmcnt(2)
	v_pk_fma_f32 v[38:39], v[22:23], v[188:189], v[46:47]
	v_pk_fma_f32 v[40:41], v[20:21], v[186:187], v[182:183]
	v_pk_fma_f32 v[34:35], v[8:9], v[166:167], v[34:35]
	v_pk_fma_f32 v[36:37], v[10:11], v[168:169], v[36:37]
	s_waitcnt lgkmcnt(1)
	v_pk_fma_f32 v[38:39], v[26:27], v[192:193], v[38:39]
	v_add_u32_e32 v32, 0x2800, v61
	v_pk_fma_f32 v[40:41], v[24:25], v[190:191], v[40:41]
	v_pk_fma_f32 v[36:37], v[14:15], v[172:173], v[36:37]
	v_pk_fma_f32 v[34:35], v[12:13], v[170:171], v[34:35]
	s_waitcnt lgkmcnt(0)
	v_pk_fma_f32 v[38:39], v[30:31], v[196:197], v[38:39]
	ds_read2_b32 v[198:199], v32 offset0:64 offset1:96
	ds_read_b32 v33, v158 offset:11264
	ds_read_b64 v[170:171], v50 offset:20800
	v_pk_fma_f32 v[40:41], v[28:29], v[194:195], v[40:41]
	v_add_f32_e32 v32, v34, v35
	v_add_f32_e32 v34, v36, v37
	v_add_f32_e32 v35, v38, v39
	v_pk_fma_f32 v[36:37], v[2:3], v[44:45], 0 op_sel_hi:[1,1,0]
	v_pk_fma_f32 v[38:39], v[0:1], v[42:43], 0 op_sel_hi:[1,1,0]
	v_add_f32_e32 v32, v32, v34
	v_add_f32_e32 v34, v40, v41
	v_pk_fma_f32 v[36:37], v[6:7], v[164:165], v[36:37]
	v_pk_fma_f32 v[38:39], v[4:5], v[162:163], v[38:39]
	v_add_f32_e32 v34, v34, v35
	v_pk_fma_f32 v[38:39], v[8:9], v[174:175], v[38:39]
	v_pk_fma_f32 v[36:37], v[10:11], v[176:177], v[36:37]
	v_add_f32_e32 v32, v32, v34
	v_pk_fma_f32 v[166:167], v[14:15], v[180:181], v[36:37]
	v_pk_fma_f32 v[168:169], v[12:13], v[178:179], v[38:39]
	ds_read_b128 v[36:39], v59 offset:11136
	ds_read_b128 v[40:43], v59 offset:11168
	ds_read_b128 v[44:47], v59 offset:11200
	ds_read_b128 v[162:165], v59 offset:11232
	v_mov_b32_e32 v34, v32
	s_nop 1
	v_permlane32_swap_b32_e32 v32, v34
	s_waitcnt lgkmcnt(3)
	v_pk_fma_f32 v[38:39], v[18:19], v[38:39], 0 op_sel_hi:[1,1,0]
	v_pk_fma_f32 v[36:37], v[16:17], v[36:37], 0 op_sel_hi:[1,1,0]
	v_add_f32_e32 v35, v32, v34
	s_waitcnt lgkmcnt(2)
	v_pk_fma_f32 v[38:39], v[22:23], v[42:43], v[38:39]
	v_pk_fma_f32 v[36:37], v[20:21], v[40:41], v[36:37]
	v_cndmask_b32_e64 v32, v33, v35, s[6:7]
	s_waitcnt lgkmcnt(1)
	v_pk_fma_f32 v[36:37], v[24:25], v[44:45], v[36:37]
	v_pk_fma_f32 v[38:39], v[26:27], v[46:47], v[38:39]
	v_mfma_f32_32x32x2_f32 v[0:15], v198, v32, v[0:15]
	s_waitcnt lgkmcnt(0)
	v_fma_f32 v38, v30, v164, v38
	v_fma_f32 v39, v31, v165, v39
	v_fma_f32 v36, v28, v162, v36
	v_fma_f32 v37, v29, v163, v37
	v_add_f32_e32 v34, v166, v167
	v_mfma_f32_32x32x2_f32 v[16:31], v199, v32, v[16:31]
	v_add_f32_e32 v32, v168, v169
	v_add_f32_e32 v32, v32, v34
	v_add_f32_e32 v34, v36, v37
	v_add_f32_e32 v36, v38, v39
	v_add_f32_e32 v34, v34, v36
	v_add_f32_e32 v32, v32, v34
	v_mov_b32_e32 v34, v32
	s_nop 1
	v_permlane32_swap_b32_e32 v32, v34
	s_and_saveexec_b64 s[28:29], s[6:7]
	s_cbranch_execz .LBB0_519
	s_add_i32 s39, s26, 8
	s_add_i32 s41, s30, 31
	s_and_b64 s[34:35], s[8:9], exec
	s_cselect_b32 s34, s39, s41
	s_waitcnt lgkmcnt(0)
	v_mul_f32_e32 v35, v35, v170
	v_mul_f32_e32 v33, v33, v171
	v_pk_add_f32 v[32:33], v[32:33], v[34:35]
	s_ashr_i32 s35, s34, 31
	v_add_f32_e32 v34, v32, v33
	v_lshl_add_u64 v[32:33], v[66:67], 0, s[34:35]
	v_lshlrev_b64 v[32:33], 11, v[32:33]
	v_lshl_add_u64 v[32:33], v[68:69], 0, v[32:33]
	global_store_dword v[32:33], v34, off
.LBB0_519:
	s_or_b64 exec, exec, s[28:29]
	ds_read_b128 v[32:35], v59 offset:11520
	ds_read_b128 v[36:39], v59 offset:11552
	ds_read_b128 v[162:165], v59 offset:12288
	ds_read_b128 v[166:169], v59 offset:12320
	ds_read_b128 v[40:43], v59 offset:11584
	ds_read_b128 v[44:47], v59 offset:11616
	ds_read_b128 v[170:173], v59 offset:12352
	ds_read_b128 v[174:177], v59 offset:12384
	ds_read_b128 v[178:181], v59 offset:11648
	ds_read_b128 v[182:185], v59 offset:11680
	ds_read_b128 v[186:189], v59 offset:12416
	ds_read_b128 v[190:193], v59 offset:12448
	ds_read_b128 v[194:197], v59 offset:11712
	ds_read_b128 v[198:201], v59 offset:11744
	ds_read_b128 v[202:205], v59 offset:12480
	ds_read_b128 v[206:209], v59 offset:12512
	s_waitcnt lgkmcnt(14)
	v_pk_fma_f32 v[34:35], v[2:3], v[34:35], 0 op_sel_hi:[1,1,0]
	v_pk_fma_f32 v[32:33], v[0:1], v[32:33], 0 op_sel_hi:[1,1,0]
	s_waitcnt lgkmcnt(7)
	v_pk_fma_f32 v[180:181], v[18:19], v[180:181], 0 op_sel_hi:[1,1,0]
	v_pk_fma_f32 v[178:179], v[16:17], v[178:179], 0 op_sel_hi:[1,1,0]
	v_pk_fma_f32 v[34:35], v[6:7], v[38:39], v[34:35]
	v_pk_fma_f32 v[32:33], v[4:5], v[36:37], v[32:33]
	s_waitcnt lgkmcnt(6)
	v_pk_fma_f32 v[36:37], v[22:23], v[184:185], v[180:181]
	v_pk_fma_f32 v[38:39], v[20:21], v[182:183], v[178:179]
	v_pk_fma_f32 v[32:33], v[8:9], v[40:41], v[32:33]
	v_pk_fma_f32 v[34:35], v[10:11], v[42:43], v[34:35]
	s_waitcnt lgkmcnt(3)
	v_pk_fma_f32 v[38:39], v[24:25], v[194:195], v[38:39]
	v_pk_fma_f32 v[36:37], v[26:27], v[196:197], v[36:37]
	v_pk_fma_f32 v[34:35], v[14:15], v[46:47], v[34:35]
	v_pk_fma_f32 v[32:33], v[12:13], v[44:45], v[32:33]
	s_waitcnt lgkmcnt(2)
	v_pk_fma_f32 v[36:37], v[30:31], v[200:201], v[36:37]
	v_pk_fma_f32 v[38:39], v[28:29], v[198:199], v[38:39]
	v_add_f32_e32 v32, v32, v33
	v_add_f32_e32 v33, v34, v35
	v_add_u32_e32 v159, 0x2c00, v61
	v_add_f32_e32 v32, v32, v33
	v_add_f32_e32 v33, v38, v39
	v_add_f32_e32 v34, v36, v37
	ds_read2_b32 v[210:211], v159 offset0:128 offset1:160
	ds_read_b32 v159, v158 offset:12544
	ds_read_b64 v[194:195], v50 offset:20808
	v_add_f32_e32 v33, v33, v34
	v_add_f32_e32 v32, v32, v33
	v_mov_b32_e32 v33, v32
	s_nop 1
	v_permlane32_swap_b32_e32 v32, v33
	v_add_f32_e32 v161, v32, v33
	s_waitcnt lgkmcnt(0)
	v_cndmask_b32_e64 v178, v159, v161, s[6:7]
	v_pk_fma_f32 v[164:165], v[2:3], v[164:165], 0 op_sel_hi:[1,1,0]
	v_pk_fma_f32 v[162:163], v[0:1], v[162:163], 0 op_sel_hi:[1,1,0]
	v_mfma_f32_32x32x2_f32 v[32:47], v211, v178, v[16:31]
	v_fma_f32 v18, v18, v188, 0
	v_fma_f32 v19, v19, v189, 0
	v_fma_f32 v16, v16, v186, 0
	v_fma_f32 v17, v17, v187, 0
	v_fma_f32 v164, v6, v168, v164
	v_fma_f32 v165, v7, v169, v165
	v_fma_f32 v162, v4, v166, v162
	v_fma_f32 v163, v5, v167, v163
	v_fma_f32 v18, v22, v192, v18
	v_fma_f32 v19, v23, v193, v19
	v_fma_f32 v16, v20, v190, v16
	v_fma_f32 v17, v21, v191, v17
	v_fma_f32 v20, v8, v170, v162
	v_fma_f32 v21, v9, v171, v163
	v_pk_fma_f32 v[22:23], v[10:11], v[172:173], v[164:165]
	v_pk_fma_f32 v[20:21], v[12:13], v[174:175], v[20:21]
	v_pk_fma_f32 v[22:23], v[14:15], v[176:177], v[22:23]
	v_pk_fma_f32 v[16:17], v[24:25], v[202:203], v[16:17]
	v_pk_fma_f32 v[18:19], v[26:27], v[204:205], v[18:19]
	v_pk_fma_f32 v[16:17], v[28:29], v[206:207], v[16:17]
	v_pk_fma_f32 v[18:19], v[30:31], v[208:209], v[18:19]
	v_add_f32_e32 v20, v20, v21
	v_mfma_f32_32x32x2_f32 v[0:15], v210, v178, v[0:15]
	v_add_f32_e32 v21, v22, v23
	v_add_f32_e32 v16, v16, v17
	v_add_f32_e32 v17, v18, v19
	v_add_f32_e32 v20, v20, v21
	v_add_f32_e32 v16, v16, v17
	v_add_f32_e32 v16, v20, v16
	v_mov_b32_e32 v18, v16
	s_nop 1
	v_permlane32_swap_b32_e32 v16, v18
	s_and_saveexec_b64 s[28:29], s[6:7]
	s_cbranch_execz .LBB0_521
	s_add_i32 s39, s26, 9
	s_add_i32 s41, s30, 30
	s_and_b64 s[34:35], s[8:9], exec
	s_cselect_b32 s34, s39, s41
	s_waitcnt lgkmcnt(0)
	v_mul_f32_e32 v19, v161, v194
	v_mul_f32_e32 v17, v159, v195
	v_pk_add_f32 v[16:17], v[16:17], v[18:19]
	s_ashr_i32 s35, s34, 31
	v_add_f32_e32 v18, v16, v17
	v_lshl_add_u64 v[16:17], v[66:67], 0, s[34:35]
	v_lshlrev_b64 v[16:17], 11, v[16:17]
	v_lshl_add_u64 v[16:17], v[68:69], 0, v[16:17]
	global_store_dword v[16:17], v18, off
.LBB0_521:
	s_or_b64 exec, exec, s[28:29]
	ds_read_b128 v[18:21], v59 offset:12800
	ds_read_b128 v[22:25], v59 offset:12832
	ds_read_b128 v[26:29], v59 offset:13568
	ds_read_b128 v[162:165], v59 offset:13600
	ds_read_b128 v[166:169], v59 offset:12864
	ds_read_b128 v[170:173], v59 offset:12896
	ds_read_b128 v[174:177], v59 offset:13632
	ds_read_b128 v[178:181], v59 offset:13664
	ds_read_b128 v[182:185], v59 offset:12928
	ds_read_b128 v[186:189], v59 offset:12960
	ds_read_b128 v[190:193], v59 offset:12992
	ds_read_b128 v[194:197], v59 offset:13024
	s_waitcnt lgkmcnt(11)
	v_pk_fma_f32 v[20:21], v[2:3], v[20:21], 0 op_sel_hi:[1,1,0]
	v_pk_fma_f32 v[18:19], v[0:1], v[18:19], 0 op_sel_hi:[1,1,0]
	s_waitcnt lgkmcnt(3)
	v_pk_fma_f32 v[30:31], v[34:35], v[184:185], 0 op_sel_hi:[1,1,0]
	v_pk_fma_f32 v[182:183], v[32:33], v[182:183], 0 op_sel_hi:[1,1,0]
	v_pk_fma_f32 v[20:21], v[6:7], v[24:25], v[20:21]
	v_pk_fma_f32 v[18:19], v[4:5], v[22:23], v[18:19]
	s_waitcnt lgkmcnt(2)
	v_pk_fma_f32 v[22:23], v[38:39], v[188:189], v[30:31]
	v_pk_fma_f32 v[24:25], v[36:37], v[186:187], v[182:183]
	v_pk_fma_f32 v[18:19], v[8:9], v[166:167], v[18:19]
	v_pk_fma_f32 v[20:21], v[10:11], v[168:169], v[20:21]
	s_waitcnt lgkmcnt(1)
	v_pk_fma_f32 v[22:23], v[42:43], v[192:193], v[22:23]
	v_add_u32_e32 v16, 0x3000, v61
	v_pk_fma_f32 v[24:25], v[40:41], v[190:191], v[24:25]
	v_pk_fma_f32 v[20:21], v[14:15], v[172:173], v[20:21]
	v_pk_fma_f32 v[18:19], v[12:13], v[170:171], v[18:19]
	s_waitcnt lgkmcnt(0)
	v_pk_fma_f32 v[22:23], v[46:47], v[196:197], v[22:23]
	ds_read2_b32 v[198:199], v16 offset0:192 offset1:224
	ds_read_b32 v17, v158 offset:13824
	ds_read_b64 v[170:171], v50 offset:20816
	v_pk_fma_f32 v[24:25], v[44:45], v[194:195], v[24:25]
	v_add_f32_e32 v16, v18, v19
	v_add_f32_e32 v18, v20, v21
	v_add_f32_e32 v19, v22, v23
	v_pk_fma_f32 v[20:21], v[2:3], v[28:29], 0 op_sel_hi:[1,1,0]
	v_pk_fma_f32 v[22:23], v[0:1], v[26:27], 0 op_sel_hi:[1,1,0]
	v_add_f32_e32 v16, v16, v18
	v_add_f32_e32 v18, v24, v25
	v_pk_fma_f32 v[20:21], v[6:7], v[164:165], v[20:21]
	v_pk_fma_f32 v[22:23], v[4:5], v[162:163], v[22:23]
	v_add_f32_e32 v18, v18, v19
	v_pk_fma_f32 v[22:23], v[8:9], v[174:175], v[22:23]
	v_pk_fma_f32 v[20:21], v[10:11], v[176:177], v[20:21]
	v_add_f32_e32 v16, v16, v18
	v_pk_fma_f32 v[166:167], v[14:15], v[180:181], v[20:21]
	v_pk_fma_f32 v[168:169], v[12:13], v[178:179], v[22:23]
	ds_read_b128 v[20:23], v59 offset:13696
	ds_read_b128 v[24:27], v59 offset:13728
	ds_read_b128 v[28:31], v59 offset:13760
	ds_read_b128 v[162:165], v59 offset:13792
	v_mov_b32_e32 v18, v16
	s_nop 1
	v_permlane32_swap_b32_e32 v16, v18
	s_waitcnt lgkmcnt(3)
	v_pk_fma_f32 v[22:23], v[34:35], v[22:23], 0 op_sel_hi:[1,1,0]
	v_pk_fma_f32 v[20:21], v[32:33], v[20:21], 0 op_sel_hi:[1,1,0]
	v_add_f32_e32 v19, v16, v18
	s_waitcnt lgkmcnt(2)
	v_pk_fma_f32 v[22:23], v[38:39], v[26:27], v[22:23]
	v_pk_fma_f32 v[20:21], v[36:37], v[24:25], v[20:21]
	v_cndmask_b32_e64 v16, v17, v19, s[6:7]
	s_waitcnt lgkmcnt(1)
	v_pk_fma_f32 v[20:21], v[40:41], v[28:29], v[20:21]
	v_pk_fma_f32 v[22:23], v[42:43], v[30:31], v[22:23]
	v_mfma_f32_32x32x2_f32 v[0:15], v198, v16, v[0:15]
	s_waitcnt lgkmcnt(0)
	v_fma_f32 v22, v46, v164, v22
	v_fma_f32 v23, v47, v165, v23
	v_fma_f32 v20, v44, v162, v20
	v_fma_f32 v21, v45, v163, v21
	v_add_f32_e32 v18, v166, v167
	v_mfma_f32_32x32x2_f32 v[32:47], v199, v16, v[32:47]
	v_add_f32_e32 v16, v168, v169
	v_add_f32_e32 v16, v16, v18
	v_add_f32_e32 v18, v20, v21
	v_add_f32_e32 v20, v22, v23
	v_add_f32_e32 v18, v18, v20
	v_add_f32_e32 v16, v16, v18
	v_mov_b32_e32 v18, v16
	s_nop 1
	v_permlane32_swap_b32_e32 v16, v18
	s_and_saveexec_b64 s[28:29], s[6:7]
	s_cbranch_execz .LBB0_523
	s_add_i32 s39, s26, 10
	s_add_i32 s41, s30, 29
	s_and_b64 s[34:35], s[8:9], exec
	s_cselect_b32 s34, s39, s41
	s_waitcnt lgkmcnt(0)
	v_mul_f32_e32 v19, v19, v170
	v_mul_f32_e32 v17, v17, v171
	v_pk_add_f32 v[16:17], v[16:17], v[18:19]
	s_ashr_i32 s35, s34, 31
	v_add_f32_e32 v18, v16, v17
	v_lshl_add_u64 v[16:17], v[66:67], 0, s[34:35]
	v_lshlrev_b64 v[16:17], 11, v[16:17]
	v_lshl_add_u64 v[16:17], v[68:69], 0, v[16:17]
	global_store_dword v[16:17], v18, off
.LBB0_523:
	s_or_b64 exec, exec, s[28:29]
	ds_read_b128 v[16:19], v59 offset:14080
	ds_read_b128 v[20:23], v59 offset:14112
	ds_read_b128 v[162:165], v59 offset:14848
	ds_read_b128 v[166:169], v59 offset:14880
	ds_read_b128 v[24:27], v59 offset:14144
	ds_read_b128 v[28:31], v59 offset:14176
	ds_read_b128 v[170:173], v59 offset:14912
	ds_read_b128 v[174:177], v59 offset:14944
	ds_read_b128 v[178:181], v59 offset:14208
	ds_read_b128 v[182:185], v59 offset:14240
	ds_read_b128 v[186:189], v59 offset:14976
	ds_read_b128 v[190:193], v59 offset:15008
	ds_read_b128 v[194:197], v59 offset:14272
	ds_read_b128 v[198:201], v59 offset:14304
	ds_read_b128 v[202:205], v59 offset:15040
	ds_read_b128 v[206:209], v59 offset:15072
	s_waitcnt lgkmcnt(14)
	v_pk_fma_f32 v[18:19], v[2:3], v[18:19], 0 op_sel_hi:[1,1,0]
	v_pk_fma_f32 v[16:17], v[0:1], v[16:17], 0 op_sel_hi:[1,1,0]
	s_waitcnt lgkmcnt(7)
	v_pk_fma_f32 v[180:181], v[34:35], v[180:181], 0 op_sel_hi:[1,1,0]
	v_pk_fma_f32 v[178:179], v[32:33], v[178:179], 0 op_sel_hi:[1,1,0]
	v_pk_fma_f32 v[18:19], v[6:7], v[22:23], v[18:19]
	v_pk_fma_f32 v[16:17], v[4:5], v[20:21], v[16:17]
	s_waitcnt lgkmcnt(6)
	v_pk_fma_f32 v[20:21], v[38:39], v[184:185], v[180:181]
	v_pk_fma_f32 v[22:23], v[36:37], v[182:183], v[178:179]
	v_pk_fma_f32 v[16:17], v[8:9], v[24:25], v[16:17]
	v_pk_fma_f32 v[18:19], v[10:11], v[26:27], v[18:19]
	s_waitcnt lgkmcnt(3)
	v_pk_fma_f32 v[22:23], v[40:41], v[194:195], v[22:23]
	v_pk_fma_f32 v[20:21], v[42:43], v[196:197], v[20:21]
	v_pk_fma_f32 v[18:19], v[14:15], v[30:31], v[18:19]
	v_pk_fma_f32 v[16:17], v[12:13], v[28:29], v[16:17]
	s_waitcnt lgkmcnt(2)
	v_pk_fma_f32 v[20:21], v[46:47], v[200:201], v[20:21]
	v_pk_fma_f32 v[22:23], v[44:45], v[198:199], v[22:23]
	v_add_f32_e32 v16, v16, v17
	v_add_f32_e32 v17, v18, v19
	v_add_u32_e32 v159, 0x3800, v61
	v_add_f32_e32 v16, v16, v17
	v_add_f32_e32 v17, v22, v23
	v_add_f32_e32 v18, v20, v21
	ds_read2_b32 v[210:211], v159 offset1:32
	ds_read_b32 v159, v158 offset:15104
	ds_read_b64 v[194:195], v50 offset:20824
	v_add_f32_e32 v17, v17, v18
	v_add_f32_e32 v16, v16, v17
	v_mov_b32_e32 v17, v16
	s_nop 1
	v_permlane32_swap_b32_e32 v16, v17
	v_add_f32_e32 v161, v16, v17
	s_waitcnt lgkmcnt(0)
	v_cndmask_b32_e64 v178, v159, v161, s[6:7]
	v_pk_fma_f32 v[164:165], v[2:3], v[164:165], 0 op_sel_hi:[1,1,0]
	v_pk_fma_f32 v[162:163], v[0:1], v[162:163], 0 op_sel_hi:[1,1,0]
	v_mfma_f32_32x32x2_f32 v[16:31], v211, v178, v[32:47]
	v_fma_f32 v34, v34, v188, 0
	v_fma_f32 v35, v35, v189, 0
	v_fma_f32 v32, v32, v186, 0
	v_fma_f32 v33, v33, v187, 0
	v_fma_f32 v164, v6, v168, v164
	v_fma_f32 v165, v7, v169, v165
	v_fma_f32 v162, v4, v166, v162
	v_fma_f32 v163, v5, v167, v163
	v_fma_f32 v34, v38, v192, v34
	v_fma_f32 v35, v39, v193, v35
	v_fma_f32 v32, v36, v190, v32
	v_fma_f32 v33, v37, v191, v33
	v_fma_f32 v36, v8, v170, v162
	v_fma_f32 v37, v9, v171, v163
	v_pk_fma_f32 v[38:39], v[10:11], v[172:173], v[164:165]
	v_pk_fma_f32 v[36:37], v[12:13], v[174:175], v[36:37]
	v_pk_fma_f32 v[38:39], v[14:15], v[176:177], v[38:39]
	v_pk_fma_f32 v[32:33], v[40:41], v[202:203], v[32:33]
	v_pk_fma_f32 v[34:35], v[42:43], v[204:205], v[34:35]
	v_pk_fma_f32 v[32:33], v[44:45], v[206:207], v[32:33]
	v_pk_fma_f32 v[34:35], v[46:47], v[208:209], v[34:35]
	v_add_f32_e32 v36, v36, v37
	v_mfma_f32_32x32x2_f32 v[0:15], v210, v178, v[0:15]
	v_add_f32_e32 v37, v38, v39
	v_add_f32_e32 v32, v32, v33
	v_add_f32_e32 v33, v34, v35
	v_add_f32_e32 v36, v36, v37
	v_add_f32_e32 v32, v32, v33
	v_add_f32_e32 v32, v36, v32
	v_mov_b32_e32 v34, v32
	s_nop 1
	v_permlane32_swap_b32_e32 v32, v34
	s_and_saveexec_b64 s[28:29], s[6:7]
	s_cbranch_execz .LBB0_525
	s_add_i32 s39, s26, 11
	s_add_i32 s41, s30, 28
	s_and_b64 s[34:35], s[8:9], exec
	s_cselect_b32 s34, s39, s41
	s_waitcnt lgkmcnt(0)
	v_mul_f32_e32 v35, v161, v194
	v_mul_f32_e32 v33, v159, v195
	v_pk_add_f32 v[32:33], v[32:33], v[34:35]
	s_ashr_i32 s35, s34, 31
	v_add_f32_e32 v34, v32, v33
	v_lshl_add_u64 v[32:33], v[66:67], 0, s[34:35]
	v_lshlrev_b64 v[32:33], 11, v[32:33]
	v_lshl_add_u64 v[32:33], v[68:69], 0, v[32:33]
	global_store_dword v[32:33], v34, off
.LBB0_525:
	s_or_b64 exec, exec, s[28:29]
	ds_read_b128 v[34:37], v59 offset:15360
	ds_read_b128 v[38:41], v59 offset:15392
	ds_read_b128 v[42:45], v59 offset:16128
	ds_read_b128 v[162:165], v59 offset:16160
	ds_read_b128 v[166:169], v59 offset:15424
	ds_read_b128 v[170:173], v59 offset:15456
	ds_read_b128 v[174:177], v59 offset:16192
	ds_read_b128 v[178:181], v59 offset:16224
	ds_read_b128 v[182:185], v59 offset:15488
	ds_read_b128 v[186:189], v59 offset:15520
	ds_read_b128 v[190:193], v59 offset:15552
	ds_read_b128 v[194:197], v59 offset:15584
	s_waitcnt lgkmcnt(11)
	v_pk_fma_f32 v[36:37], v[2:3], v[36:37], 0 op_sel_hi:[1,1,0]
	v_pk_fma_f32 v[34:35], v[0:1], v[34:35], 0 op_sel_hi:[1,1,0]
	s_waitcnt lgkmcnt(3)
	v_pk_fma_f32 v[46:47], v[18:19], v[184:185], 0 op_sel_hi:[1,1,0]
	v_pk_fma_f32 v[182:183], v[16:17], v[182:183], 0 op_sel_hi:[1,1,0]
	v_pk_fma_f32 v[36:37], v[6:7], v[40:41], v[36:37]
	v_pk_fma_f32 v[34:35], v[4:5], v[38:39], v[34:35]
	s_waitcnt lgkmcnt(2)
	v_pk_fma_f32 v[38:39], v[22:23], v[188:189], v[46:47]
	v_pk_fma_f32 v[40:41], v[20:21], v[186:187], v[182:183]
	v_pk_fma_f32 v[34:35], v[8:9], v[166:167], v[34:35]
	v_pk_fma_f32 v[36:37], v[10:11], v[168:169], v[36:37]
	s_waitcnt lgkmcnt(1)
	v_pk_fma_f32 v[38:39], v[26:27], v[192:193], v[38:39]
	v_add_u32_e32 v32, 0x3c00, v61
	v_pk_fma_f32 v[40:41], v[24:25], v[190:191], v[40:41]
	v_pk_fma_f32 v[36:37], v[14:15], v[172:173], v[36:37]
	v_pk_fma_f32 v[34:35], v[12:13], v[170:171], v[34:35]
	s_waitcnt lgkmcnt(0)
	v_pk_fma_f32 v[38:39], v[30:31], v[196:197], v[38:39]
	ds_read2_b32 v[198:199], v32 offset0:64 offset1:96
	ds_read_b32 v33, v158 offset:16384
	ds_read_b64 v[170:171], v50 offset:20832
	v_pk_fma_f32 v[40:41], v[28:29], v[194:195], v[40:41]
	v_add_f32_e32 v32, v34, v35
	v_add_f32_e32 v34, v36, v37
	v_add_f32_e32 v35, v38, v39
	v_pk_fma_f32 v[36:37], v[2:3], v[44:45], 0 op_sel_hi:[1,1,0]
	v_pk_fma_f32 v[38:39], v[0:1], v[42:43], 0 op_sel_hi:[1,1,0]
	v_add_f32_e32 v32, v32, v34
	v_add_f32_e32 v34, v40, v41
	v_pk_fma_f32 v[36:37], v[6:7], v[164:165], v[36:37]
	v_pk_fma_f32 v[38:39], v[4:5], v[162:163], v[38:39]
	v_add_f32_e32 v34, v34, v35
	v_pk_fma_f32 v[38:39], v[8:9], v[174:175], v[38:39]
	v_pk_fma_f32 v[36:37], v[10:11], v[176:177], v[36:37]
	v_add_f32_e32 v32, v32, v34
	v_pk_fma_f32 v[166:167], v[14:15], v[180:181], v[36:37]
	v_pk_fma_f32 v[168:169], v[12:13], v[178:179], v[38:39]
	ds_read_b128 v[36:39], v59 offset:16256
	ds_read_b128 v[40:43], v59 offset:16288
	ds_read_b128 v[44:47], v59 offset:16320
	ds_read_b128 v[162:165], v59 offset:16352
	v_mov_b32_e32 v34, v32
	s_nop 1
	v_permlane32_swap_b32_e32 v32, v34
	s_waitcnt lgkmcnt(3)
	v_pk_fma_f32 v[38:39], v[18:19], v[38:39], 0 op_sel_hi:[1,1,0]
	v_pk_fma_f32 v[36:37], v[16:17], v[36:37], 0 op_sel_hi:[1,1,0]
	v_add_f32_e32 v35, v32, v34
	s_waitcnt lgkmcnt(2)
	v_pk_fma_f32 v[38:39], v[22:23], v[42:43], v[38:39]
	v_pk_fma_f32 v[36:37], v[20:21], v[40:41], v[36:37]
	v_cndmask_b32_e64 v32, v33, v35, s[6:7]
	s_waitcnt lgkmcnt(1)
	v_pk_fma_f32 v[36:37], v[24:25], v[44:45], v[36:37]
	v_pk_fma_f32 v[38:39], v[26:27], v[46:47], v[38:39]
	v_mfma_f32_32x32x2_f32 v[0:15], v198, v32, v[0:15]
	s_waitcnt lgkmcnt(0)
	v_fma_f32 v38, v30, v164, v38
	v_fma_f32 v39, v31, v165, v39
	v_fma_f32 v36, v28, v162, v36
	v_fma_f32 v37, v29, v163, v37
	v_add_f32_e32 v34, v166, v167
	v_mfma_f32_32x32x2_f32 v[16:31], v199, v32, v[16:31]
	v_add_f32_e32 v32, v168, v169
	v_add_f32_e32 v32, v32, v34
	v_add_f32_e32 v34, v36, v37
	v_add_f32_e32 v36, v38, v39
	v_add_f32_e32 v34, v34, v36
	v_add_f32_e32 v32, v32, v34
	v_mov_b32_e32 v34, v32
	s_nop 1
	v_permlane32_swap_b32_e32 v32, v34
	s_and_saveexec_b64 s[28:29], s[6:7]
	s_cbranch_execz .LBB0_527
	s_add_i32 s39, s26, 12
	s_add_i32 s41, s30, 27
	s_and_b64 s[34:35], s[8:9], exec
	s_cselect_b32 s34, s39, s41
	s_waitcnt lgkmcnt(0)
	v_mul_f32_e32 v35, v35, v170
	v_mul_f32_e32 v33, v33, v171
	v_pk_add_f32 v[32:33], v[32:33], v[34:35]
	s_ashr_i32 s35, s34, 31
	v_add_f32_e32 v34, v32, v33
	v_lshl_add_u64 v[32:33], v[66:67], 0, s[34:35]
	v_lshlrev_b64 v[32:33], 11, v[32:33]
	v_lshl_add_u64 v[32:33], v[68:69], 0, v[32:33]
	global_store_dword v[32:33], v34, off
.LBB0_527:
	s_or_b64 exec, exec, s[28:29]
	ds_read_b128 v[32:35], v59 offset:16640
	ds_read_b128 v[36:39], v59 offset:16672
	ds_read_b128 v[162:165], v59 offset:17408
	ds_read_b128 v[166:169], v59 offset:17440
	ds_read_b128 v[40:43], v59 offset:16704
	ds_read_b128 v[44:47], v59 offset:16736
	ds_read_b128 v[170:173], v59 offset:17472
	ds_read_b128 v[174:177], v59 offset:17504
	ds_read_b128 v[178:181], v59 offset:16768
	ds_read_b128 v[182:185], v59 offset:16800
	ds_read_b128 v[186:189], v59 offset:17536
	ds_read_b128 v[190:193], v59 offset:17568
	ds_read_b128 v[194:197], v59 offset:16832
	ds_read_b128 v[198:201], v59 offset:16864
	ds_read_b128 v[202:205], v59 offset:17600
	ds_read_b128 v[206:209], v59 offset:17632
	s_waitcnt lgkmcnt(14)
	v_pk_fma_f32 v[34:35], v[2:3], v[34:35], 0 op_sel_hi:[1,1,0]
	v_pk_fma_f32 v[32:33], v[0:1], v[32:33], 0 op_sel_hi:[1,1,0]
	s_waitcnt lgkmcnt(7)
	v_pk_fma_f32 v[180:181], v[18:19], v[180:181], 0 op_sel_hi:[1,1,0]
	v_pk_fma_f32 v[178:179], v[16:17], v[178:179], 0 op_sel_hi:[1,1,0]
	v_pk_fma_f32 v[34:35], v[6:7], v[38:39], v[34:35]
	v_pk_fma_f32 v[32:33], v[4:5], v[36:37], v[32:33]
	s_waitcnt lgkmcnt(6)
	v_pk_fma_f32 v[36:37], v[22:23], v[184:185], v[180:181]
	v_pk_fma_f32 v[38:39], v[20:21], v[182:183], v[178:179]
	v_pk_fma_f32 v[32:33], v[8:9], v[40:41], v[32:33]
	v_pk_fma_f32 v[34:35], v[10:11], v[42:43], v[34:35]
	s_waitcnt lgkmcnt(3)
	v_pk_fma_f32 v[38:39], v[24:25], v[194:195], v[38:39]
	v_pk_fma_f32 v[36:37], v[26:27], v[196:197], v[36:37]
	v_pk_fma_f32 v[34:35], v[14:15], v[46:47], v[34:35]
	v_pk_fma_f32 v[32:33], v[12:13], v[44:45], v[32:33]
	s_waitcnt lgkmcnt(2)
	v_pk_fma_f32 v[36:37], v[30:31], v[200:201], v[36:37]
	v_pk_fma_f32 v[38:39], v[28:29], v[198:199], v[38:39]
	v_add_f32_e32 v32, v32, v33
	v_add_f32_e32 v33, v34, v35
	v_add_u32_e32 v159, 0x4000, v61
	v_add_f32_e32 v32, v32, v33
	v_add_f32_e32 v33, v38, v39
	v_add_f32_e32 v34, v36, v37
	ds_read2_b32 v[210:211], v159 offset0:128 offset1:160
	ds_read_b32 v159, v158 offset:17664
	ds_read_b64 v[194:195], v50 offset:20840
	v_add_f32_e32 v33, v33, v34
	v_add_f32_e32 v32, v32, v33
	v_mov_b32_e32 v33, v32
	s_nop 1
	v_permlane32_swap_b32_e32 v32, v33
	v_add_f32_e32 v161, v32, v33
	s_waitcnt lgkmcnt(0)
	v_cndmask_b32_e64 v178, v159, v161, s[6:7]
	v_pk_fma_f32 v[164:165], v[2:3], v[164:165], 0 op_sel_hi:[1,1,0]
	v_pk_fma_f32 v[162:163], v[0:1], v[162:163], 0 op_sel_hi:[1,1,0]
	v_mfma_f32_32x32x2_f32 v[32:47], v211, v178, v[16:31]
	v_fma_f32 v18, v18, v188, 0
	v_fma_f32 v19, v19, v189, 0
	v_fma_f32 v16, v16, v186, 0
	v_fma_f32 v17, v17, v187, 0
	v_fma_f32 v164, v6, v168, v164
	v_fma_f32 v165, v7, v169, v165
	v_fma_f32 v162, v4, v166, v162
	v_fma_f32 v163, v5, v167, v163
	v_fma_f32 v18, v22, v192, v18
	v_fma_f32 v19, v23, v193, v19
	v_fma_f32 v16, v20, v190, v16
	v_fma_f32 v17, v21, v191, v17
	v_fma_f32 v20, v8, v170, v162
	v_fma_f32 v21, v9, v171, v163
	v_pk_fma_f32 v[22:23], v[10:11], v[172:173], v[164:165]
	v_pk_fma_f32 v[20:21], v[12:13], v[174:175], v[20:21]
	v_pk_fma_f32 v[22:23], v[14:15], v[176:177], v[22:23]
	v_pk_fma_f32 v[16:17], v[24:25], v[202:203], v[16:17]
	v_pk_fma_f32 v[18:19], v[26:27], v[204:205], v[18:19]
	v_pk_fma_f32 v[16:17], v[28:29], v[206:207], v[16:17]
	v_pk_fma_f32 v[18:19], v[30:31], v[208:209], v[18:19]
	v_add_f32_e32 v20, v20, v21
	v_mfma_f32_32x32x2_f32 v[0:15], v210, v178, v[0:15]
	v_add_f32_e32 v21, v22, v23
	v_add_f32_e32 v16, v16, v17
	v_add_f32_e32 v17, v18, v19
	v_add_f32_e32 v20, v20, v21
	v_add_f32_e32 v16, v16, v17
	v_add_f32_e32 v16, v20, v16
	v_mov_b32_e32 v18, v16
	s_nop 1
	v_permlane32_swap_b32_e32 v16, v18
	s_and_saveexec_b64 s[28:29], s[6:7]
	s_cbranch_execz .LBB0_529
	s_add_i32 s39, s26, 13
	s_add_i32 s41, s30, 26
	s_and_b64 s[34:35], s[8:9], exec
	s_cselect_b32 s34, s39, s41
	s_waitcnt lgkmcnt(0)
	v_mul_f32_e32 v19, v161, v194
	v_mul_f32_e32 v17, v159, v195
	v_pk_add_f32 v[16:17], v[16:17], v[18:19]
	s_ashr_i32 s35, s34, 31
	v_add_f32_e32 v18, v16, v17
	v_lshl_add_u64 v[16:17], v[66:67], 0, s[34:35]
	v_lshlrev_b64 v[16:17], 11, v[16:17]
	v_lshl_add_u64 v[16:17], v[68:69], 0, v[16:17]
	global_store_dword v[16:17], v18, off
.LBB0_529:
	s_or_b64 exec, exec, s[28:29]
	ds_read_b128 v[18:21], v59 offset:17920
	ds_read_b128 v[22:25], v59 offset:17952
	ds_read_b128 v[26:29], v59 offset:18688
	ds_read_b128 v[162:165], v59 offset:18720
	ds_read_b128 v[166:169], v59 offset:17984
	ds_read_b128 v[170:173], v59 offset:18016
	ds_read_b128 v[174:177], v59 offset:18752
	ds_read_b128 v[178:181], v59 offset:18784
	ds_read_b128 v[182:185], v59 offset:18048
	ds_read_b128 v[186:189], v59 offset:18080
	ds_read_b128 v[190:193], v59 offset:18112
	ds_read_b128 v[194:197], v59 offset:18144
	s_waitcnt lgkmcnt(11)
	v_pk_fma_f32 v[20:21], v[2:3], v[20:21], 0 op_sel_hi:[1,1,0]
	v_pk_fma_f32 v[18:19], v[0:1], v[18:19], 0 op_sel_hi:[1,1,0]
	s_waitcnt lgkmcnt(3)
	v_pk_fma_f32 v[30:31], v[34:35], v[184:185], 0 op_sel_hi:[1,1,0]
	v_pk_fma_f32 v[182:183], v[32:33], v[182:183], 0 op_sel_hi:[1,1,0]
	v_pk_fma_f32 v[20:21], v[6:7], v[24:25], v[20:21]
	v_pk_fma_f32 v[18:19], v[4:5], v[22:23], v[18:19]
	s_waitcnt lgkmcnt(2)
	v_pk_fma_f32 v[22:23], v[38:39], v[188:189], v[30:31]
	v_pk_fma_f32 v[24:25], v[36:37], v[186:187], v[182:183]
	v_pk_fma_f32 v[18:19], v[8:9], v[166:167], v[18:19]
	v_pk_fma_f32 v[20:21], v[10:11], v[168:169], v[20:21]
	s_waitcnt lgkmcnt(1)
	v_pk_fma_f32 v[22:23], v[42:43], v[192:193], v[22:23]
	v_add_u32_e32 v16, 0x4400, v61
	v_pk_fma_f32 v[24:25], v[40:41], v[190:191], v[24:25]
	v_pk_fma_f32 v[20:21], v[14:15], v[172:173], v[20:21]
	v_pk_fma_f32 v[18:19], v[12:13], v[170:171], v[18:19]
	s_waitcnt lgkmcnt(0)
	v_pk_fma_f32 v[22:23], v[46:47], v[196:197], v[22:23]
	ds_read2_b32 v[198:199], v16 offset0:192 offset1:224
	ds_read_b32 v17, v158 offset:18944
	ds_read_b64 v[170:171], v50 offset:20848
	v_pk_fma_f32 v[24:25], v[44:45], v[194:195], v[24:25]
	v_add_f32_e32 v16, v18, v19
	v_add_f32_e32 v18, v20, v21
	v_add_f32_e32 v19, v22, v23
	v_pk_fma_f32 v[20:21], v[2:3], v[28:29], 0 op_sel_hi:[1,1,0]
	v_pk_fma_f32 v[22:23], v[0:1], v[26:27], 0 op_sel_hi:[1,1,0]
	v_add_f32_e32 v16, v16, v18
	v_add_f32_e32 v18, v24, v25
	v_pk_fma_f32 v[20:21], v[6:7], v[164:165], v[20:21]
	v_pk_fma_f32 v[22:23], v[4:5], v[162:163], v[22:23]
	v_add_f32_e32 v18, v18, v19
	v_pk_fma_f32 v[22:23], v[8:9], v[174:175], v[22:23]
	v_pk_fma_f32 v[20:21], v[10:11], v[176:177], v[20:21]
	v_add_f32_e32 v16, v16, v18
	v_pk_fma_f32 v[166:167], v[14:15], v[180:181], v[20:21]
	v_pk_fma_f32 v[168:169], v[12:13], v[178:179], v[22:23]
	ds_read_b128 v[20:23], v59 offset:18816
	ds_read_b128 v[24:27], v59 offset:18848
	ds_read_b128 v[28:31], v59 offset:18880
	ds_read_b128 v[162:165], v59 offset:18912
	v_mov_b32_e32 v18, v16
	s_nop 1
	v_permlane32_swap_b32_e32 v16, v18
	s_waitcnt lgkmcnt(3)
	v_pk_fma_f32 v[22:23], v[34:35], v[22:23], 0 op_sel_hi:[1,1,0]
	v_pk_fma_f32 v[20:21], v[32:33], v[20:21], 0 op_sel_hi:[1,1,0]
	v_add_f32_e32 v19, v16, v18
	s_waitcnt lgkmcnt(2)
	v_pk_fma_f32 v[22:23], v[38:39], v[26:27], v[22:23]
	v_pk_fma_f32 v[20:21], v[36:37], v[24:25], v[20:21]
	v_cndmask_b32_e64 v16, v17, v19, s[6:7]
	s_waitcnt lgkmcnt(1)
	v_pk_fma_f32 v[20:21], v[40:41], v[28:29], v[20:21]
	v_pk_fma_f32 v[22:23], v[42:43], v[30:31], v[22:23]
	v_mfma_f32_32x32x2_f32 v[0:15], v198, v16, v[0:15]
	s_waitcnt lgkmcnt(0)
	v_fma_f32 v22, v46, v164, v22
	v_fma_f32 v23, v47, v165, v23
	v_fma_f32 v20, v44, v162, v20
	v_fma_f32 v21, v45, v163, v21
	v_add_f32_e32 v18, v166, v167
	v_mfma_f32_32x32x2_f32 v[32:47], v199, v16, v[32:47]
	v_add_f32_e32 v16, v168, v169
	v_add_f32_e32 v16, v16, v18
	v_add_f32_e32 v18, v20, v21
	v_add_f32_e32 v20, v22, v23
	v_add_f32_e32 v18, v18, v20
	v_add_f32_e32 v16, v16, v18
	v_mov_b32_e32 v18, v16
	s_nop 1
	v_permlane32_swap_b32_e32 v16, v18
	s_and_saveexec_b64 s[28:29], s[6:7]
	s_cbranch_execz .LBB0_531
	s_add_i32 s39, s26, 14
	s_add_i32 s41, s30, 25
	s_and_b64 s[34:35], s[8:9], exec
	s_cselect_b32 s34, s39, s41
	s_waitcnt lgkmcnt(0)
	v_mul_f32_e32 v19, v19, v170
	v_mul_f32_e32 v17, v17, v171
	v_pk_add_f32 v[16:17], v[16:17], v[18:19]
	s_ashr_i32 s35, s34, 31
	v_add_f32_e32 v18, v16, v17
	v_lshl_add_u64 v[16:17], v[66:67], 0, s[34:35]
	v_lshlrev_b64 v[16:17], 11, v[16:17]
	v_lshl_add_u64 v[16:17], v[68:69], 0, v[16:17]
	global_store_dword v[16:17], v18, off
